# next-unit scheduling fast path for a 256-workgroup grid; M2 scans via DPP; residual epilogue row-sum shuffles via v_permlane16/32_swap instead of ds_bpermute (P2, P7)
# baseline (speedup 1.0000x reference)
; __device__ __forceinline__ unsigned cvt_pk_bf16(float lo, float hi) { unsigned r; asm volatile("v_cvt_pk_bf16_f32 %0, %1, %2" : "=v"(r) : "v"(lo), "v"(hi)); return r; }
;     __device__ __forceinline__ void operator()(const f32x4 (&acc)[2][2][4][2], const Unit& u, int wr, int wc, int fr, int fq) const {
;     ...
;                     for (int bj = 0; bj < 2; ++bj) xin[0][m][bj] = *(const u32x4*)(xb + (size_t)(row0 + ai * HALF + m * 16) * DM + col0 + bj * HALF);
;         }
; #pragma unroll
;             for (int m = 0; m < 4; ++m) {
;                 const int row = row0 + ai * HALF + m * 16; const size_t off = (size_t)row * DM + col0; float q = 0.f;
; #pragma unroll
;                 for (int bj = 0; bj < 2; ++bj) {
;                     const size_t o2 = off + bj * HALF; f32x4 b0, b1;
;                     if (XI_BF16) bf8_to_f32(xin[0][m][bj], b0, b1); else { b0 = *(const f32x4*)(xi + o2); b1 = *(const f32x4*)(xi + o2 + 4); }
;                     const f32x4 o0 = b0 + acc[ai][bj][m][0] * scale, o1 = b1 + acc[ai][bj][m][1] * scale;
;                     u32x4 w; w.x = cvt_pk_bf16(o0[0], o0[1]); w.y = cvt_pk_bf16(o0[2], o0[3]); w.z = cvt_pk_bf16(o1[0], o1[1]); w.w = cvt_pk_bf16(o1[2], o1[3]);
;                     *(u32x4*)(xb + o2) = w;
;                     q += ((o0[0] * o0[0] + o0[1] * o0[1]) + (o0[2] * o0[2] + o0[3] * o0[3])) + ((o1[0] * o1[0] + o1[1] * o1[1]) + (o1[2] * o1[2] + o1[3] * o1[3]));
;                 }
;                 q += __shfl_xor(q, 16); q += __shfl_xor(q, 32);
;                 if (fq == 0) ssout[(size_t)row * 16 + u.pn * 4 + wc] = q;
.LBB0_375:
	v_lshl_or_b32 v128, s34, 5, v244
	v_lshl_or_b32 v184, s4, 8, v128
	v_lshl_add_u32 v188, s45, 8, v157
	v_ashrrev_i32_e32 v185, 31, v184
	v_lshlrev_b64 v[214:215], 1, v[184:185]
	v_ashrrev_i32_e32 v189, 31, v188
	v_lshl_add_u64 v[186:187], s[76:77], 0, v[214:215]
	v_lshlrev_b64 v[204:205], 11, v[188:189]
	v_lshl_add_u64 v[128:129], v[186:187], 0, v[204:205]
	global_load_dwordx4 v[206:209], v[128:129], off
	global_load_dwordx4 v[210:213], v[128:129], off offset:256
	v_or_b32_e32 v198, 16, v188
	v_or_b32_e32 v194, 32, v188
	v_or_b32_e32 v190, 48, v188
	v_ashrrev_i32_e32 v199, 31, v198
	v_ashrrev_i32_e32 v195, 31, v194
	v_ashrrev_i32_e32 v191, 31, v190
	v_lshlrev_b64 v[200:201], 11, v[198:199]
	v_lshlrev_b64 v[196:197], 11, v[194:195]
	v_lshlrev_b64 v[192:193], 11, v[190:191]
	v_lshl_add_u64 v[128:129], v[186:187], 0, v[200:201]
	v_lshl_add_u64 v[130:131], v[186:187], 0, v[196:197]
	v_lshl_add_u64 v[216:217], v[186:187], 0, v[192:193]
	global_load_dwordx4 v[148:151], v[128:129], off
	global_load_dwordx4 v[144:147], v[128:129], off offset:256
	global_load_dwordx4 v[140:143], v[130:131], off
	global_load_dwordx4 v[136:139], v[130:131], off offset:256
	global_load_dwordx4 v[132:135], v[216:217], off
	s_nop 0
	global_load_dwordx4 v[128:131], v[216:217], off offset:256
	v_and_b32_e32 v217, 64, v203
	v_xor_b32_e32 v216, 16, v203
	v_add_u32_e32 v217, 64, v217
	v_xor_b32_e32 v218, 32, v203
	v_cmp_lt_i32_e32 vcc, v216, v217
	s_lshl_b32 s20, s4, 2
	s_ashr_i32 s21, s20, 31
	v_cndmask_b32_e32 v219, v203, v216, vcc
	v_cmp_lt_i32_e32 vcc, v218, v217
	v_lshl_add_u64 v[216:217], s[76:77], 0, v[204:205]
	v_lshlrev_b32_e32 v204, 2, v219
	v_cndmask_b32_e32 v224, v203, v218, vcc
	v_lshl_add_u64 v[214:215], v[216:217], 0, v[214:215]
	s_waitcnt vmcnt(0)
	v_lshlrev_b32_e32 v216, 16, v206
	v_and_b32_e32 v217, 0xffff0000, v206
	v_lshlrev_b32_e32 v206, 16, v207
	v_and_b32_e32 v207, 0xffff0000, v207
	v_lshlrev_b32_e32 v218, 16, v208
	v_and_b32_e32 v219, 0xffff0000, v208
	v_lshlrev_b32_e32 v208, 16, v209
	v_and_b32_e32 v209, 0xffff0000, v209
	v_lshlrev_b32_e32 v220, 16, v210
	v_and_b32_e32 v221, 0xffff0000, v210
	v_lshlrev_b32_e32 v210, 16, v211
	v_and_b32_e32 v211, 0xffff0000, v211
	v_lshlrev_b32_e32 v222, 16, v212
	v_and_b32_e32 v223, 0xffff0000, v212
	v_lshlrev_b32_e32 v212, 16, v213
	v_and_b32_e32 v213, 0xffff0000, v213
	v_pk_fma_f32 v[126:127], v[126:127], 0.5, v[206:207] op_sel_hi:[1,0,1]
	v_pk_fma_f32 v[124:125], v[124:125], 0.5, v[216:217] op_sel_hi:[1,0,1]
	v_pk_fma_f32 v[122:123], v[122:123], 0.5, v[208:209] op_sel_hi:[1,0,1]
	v_pk_fma_f32 v[120:121], v[120:121], 0.5, v[218:219] op_sel_hi:[1,0,1]
	v_pk_fma_f32 v[118:119], v[118:119], 0.5, v[210:211] op_sel_hi:[1,0,1]
	v_pk_fma_f32 v[116:117], v[116:117], 0.5, v[220:221] op_sel_hi:[1,0,1]
	v_pk_fma_f32 v[206:207], v[114:115], 0.5, v[212:213] op_sel_hi:[1,0,1]
	v_pk_fma_f32 v[208:209], v[112:113], 0.5, v[222:223] op_sel_hi:[1,0,1]
	v_cvt_pk_bf16_f32 v112, v124, v125
	v_cvt_pk_bf16_f32 v113, v126, v127
	v_mul_f32_e32 v114, v125, v125
	v_mul_f32_e32 v115, v127, v127
	v_mul_f32_e32 v125, v121, v121
	v_mul_f32_e32 v127, v123, v123
	v_mul_f32_e32 v205, v117, v117
	v_mul_f32_e32 v210, v119, v119
	v_mul_f32_e32 v211, v209, v209
	v_mul_f32_e32 v212, v207, v207
	v_fmac_f32_e32 v114, v124, v124
	v_fmac_f32_e32 v115, v126, v126
	v_fmac_f32_e32 v125, v120, v120
	v_fmac_f32_e32 v127, v122, v122
	v_fmac_f32_e32 v205, v116, v116
	v_fmac_f32_e32 v210, v118, v118
	v_fmac_f32_e32 v211, v208, v208
	v_fmac_f32_e32 v212, v206, v206
	v_add_f32_e32 v114, v114, v115
	v_add_f32_e32 v115, v125, v127
	v_add_f32_e32 v124, v205, v210
	v_add_f32_e32 v125, v211, v212
	v_add_f32_e32 v114, v114, v115
	v_add_f32_e32 v115, v124, v125
	v_add_f32_e32 v124, v114, v115
	v_mov_b32_e32 v125, v124
	s_nop 1
	v_permlane16_swap_b32_e32 v124, v125
	v_cvt_pk_bf16_f32 v114, v120, v121
	v_cvt_pk_bf16_f32 v115, v122, v123
	global_store_dwordx4 v[214:215], v[112:115], off
	v_cvt_pk_bf16_f32 v116, v116, v117
	v_cvt_pk_bf16_f32 v117, v118, v119
	v_cvt_pk_bf16_f32 v118, v208, v209
	v_cvt_pk_bf16_f32 v119, v206, v207
	global_store_dwordx4 v[214:215], v[116:119], off offset:256
	s_waitcnt lgkmcnt(0)
	v_add_f32_e32 v113, v124, v125
	v_lshlrev_b32_e32 v112, 2, v224
	v_mov_b32_e32 v114, v113
	s_nop 1
	v_permlane32_swap_b32_e32 v113, v114
	s_and_saveexec_b64 s[24:25], s[8:9]
	s_cbranch_execz .LBB0_377
	v_lshlrev_b64 v[116:117], 6, v[188:189]
	v_lshl_add_u64 v[116:117], s[14:15], 0, v[116:117]
	v_lshl_add_u64 v[116:117], s[20:21], 2, v[116:117]
	s_lshl_b32 s4, s34, 2
	v_lshl_add_u64 v[116:117], v[116:117], 0, s[4:5]
	s_waitcnt lgkmcnt(0)
	v_add_f32_e32 v113, v113, v114
	global_store_dword v[116:117], v113, off
; __device__ __forceinline__ unsigned cvt_pk_bf16(float lo, float hi) { unsigned r; asm volatile("v_cvt_pk_bf16_f32 %0, %1, %2" : "=v"(r) : "v"(lo), "v"(hi)); return r; }
;     __device__ __forceinline__ void operator()(const f32x4 (&acc)[2][2][4][2], const Unit& u, int wr, int wc, int fr, int fq) const {
;     ...
; #pragma unroll
;             for (int m = 0; m < 4; ++m) {
;                 const int row = row0 + ai * HALF + m * 16; const size_t off = (size_t)row * DM + col0; float q = 0.f;
; #pragma unroll
;                 for (int bj = 0; bj < 2; ++bj) {
;                     const size_t o2 = off + bj * HALF; f32x4 b0, b1;
;                     if (XI_BF16) bf8_to_f32(xin[0][m][bj], b0, b1); else { b0 = *(const f32x4*)(xi + o2); b1 = *(const f32x4*)(xi + o2 + 4); }
;                     const f32x4 o0 = b0 + acc[ai][bj][m][0] * scale, o1 = b1 + acc[ai][bj][m][1] * scale;
;                     u32x4 w; w.x = cvt_pk_bf16(o0[0], o0[1]); w.y = cvt_pk_bf16(o0[2], o0[3]); w.z = cvt_pk_bf16(o1[0], o1[1]); w.w = cvt_pk_bf16(o1[2], o1[3]);
;                     *(u32x4*)(xb + o2) = w;
;                     q += ((o0[0] * o0[0] + o0[1] * o0[1]) + (o0[2] * o0[2] + o0[3] * o0[3])) + ((o1[0] * o1[0] + o1[1] * o1[1]) + (o1[2] * o1[2] + o1[3] * o1[3]));
;                 }
;                 q += __shfl_xor(q, 16); q += __shfl_xor(q, 32);
;                 if (fq == 0) ssout[(size_t)row * 16 + u.pn * 4 + wc] = q;
.LBB0_377:
	s_or_b64 exec, exec, s[24:25]
	s_waitcnt lgkmcnt(0)
	v_lshlrev_b32_e32 v114, 16, v148
	v_and_b32_e32 v115, 0xffff0000, v148
	v_lshlrev_b32_e32 v116, 16, v149
	v_and_b32_e32 v117, 0xffff0000, v149
	v_lshlrev_b32_e32 v118, 16, v150
	v_and_b32_e32 v119, 0xffff0000, v150
	v_pk_fma_f32 v[108:109], v[108:109], 0.5, v[114:115] op_sel_hi:[1,0,1]
	v_pk_fma_f32 v[110:111], v[110:111], 0.5, v[116:117] op_sel_hi:[1,0,1]
	v_pk_fma_f32 v[116:117], v[104:105], 0.5, v[118:119] op_sel_hi:[1,0,1]
	v_cvt_pk_bf16_f32 v104, v108, v109
	v_mul_f32_e32 v109, v109, v109
	v_lshlrev_b32_e32 v120, 16, v151
	v_and_b32_e32 v121, 0xffff0000, v151
	v_fmac_f32_e32 v109, v108, v108
	v_mul_f32_e32 v108, v111, v111
	v_pk_fma_f32 v[114:115], v[106:107], 0.5, v[120:121] op_sel_hi:[1,0,1]
	v_fmac_f32_e32 v108, v110, v110
	v_cvt_pk_bf16_f32 v105, v110, v111
	v_add_f32_e32 v108, v109, v108
	v_mul_f32_e32 v109, v117, v117
	v_mul_f32_e32 v110, v115, v115
	v_fmac_f32_e32 v109, v116, v116
	v_fmac_f32_e32 v110, v114, v114
	v_add_f32_e32 v109, v109, v110
	v_add_f32_e32 v113, v108, v109
	v_lshlrev_b32_e32 v108, 16, v144
	v_and_b32_e32 v109, 0xffff0000, v144
	v_lshlrev_b32_e32 v110, 16, v145
	v_and_b32_e32 v111, 0xffff0000, v145
	v_cvt_pk_bf16_f32 v106, v116, v117
	v_cvt_pk_bf16_f32 v107, v114, v115
	v_lshlrev_b32_e32 v114, 16, v146
	v_and_b32_e32 v115, 0xffff0000, v146
	v_pk_fma_f32 v[102:103], v[102:103], 0.5, v[110:111] op_sel_hi:[1,0,1]
	v_pk_fma_f32 v[100:101], v[100:101], 0.5, v[108:109] op_sel_hi:[1,0,1]
	v_lshlrev_b32_e32 v116, 16, v147
	v_and_b32_e32 v117, 0xffff0000, v147
	v_pk_fma_f32 v[110:111], v[96:97], 0.5, v[114:115] op_sel_hi:[1,0,1]
	v_mul_f32_e32 v96, v101, v101
	v_mul_f32_e32 v97, v103, v103
	v_pk_fma_f32 v[108:109], v[98:99], 0.5, v[116:117] op_sel_hi:[1,0,1]
	v_fmac_f32_e32 v96, v100, v100
	v_fmac_f32_e32 v97, v102, v102
	v_add_f32_e32 v96, v96, v97
	v_mul_f32_e32 v97, v111, v111
	v_mul_f32_e32 v98, v109, v109
	v_fmac_f32_e32 v97, v110, v110
	v_fmac_f32_e32 v98, v108, v108
	v_add_f32_e32 v97, v97, v98
	v_add_f32_e32 v96, v96, v97
	v_add_f32_e32 v99, v113, v96
	v_mov_b32_e32 v113, v99
	s_nop 1
	v_permlane16_swap_b32_e32 v99, v113
	v_lshl_add_u64 v[96:97], s[76:77], 0, v[200:201]
	v_lshl_add_u64 v[114:115], v[184:185], 1, v[96:97]
	global_store_dwordx4 v[114:115], v[104:107], off
	v_cvt_pk_bf16_f32 v98, v100, v101
	s_waitcnt lgkmcnt(0)
	v_add_f32_e32 v96, v99, v113
	v_mov_b32_e32 v97, v96
	s_nop 1
	v_permlane32_swap_b32_e32 v96, v97
	v_cvt_pk_bf16_f32 v99, v102, v103
	v_cvt_pk_bf16_f32 v100, v110, v111
	v_cvt_pk_bf16_f32 v101, v108, v109
	global_store_dwordx4 v[114:115], v[98:101], off offset:256
	s_and_saveexec_b64 s[24:25], s[8:9]
	s_cbranch_execz .LBB0_379
	v_lshlrev_b64 v[98:99], 6, v[198:199]
	v_lshl_add_u64 v[98:99], s[14:15], 0, v[98:99]
	v_lshl_add_u64 v[98:99], s[20:21], 2, v[98:99]
	s_lshl_b32 s4, s34, 2
	v_lshl_add_u64 v[98:99], v[98:99], 0, s[4:5]
	s_waitcnt lgkmcnt(0)
	v_add_f32_e32 v96, v96, v97
	global_store_dword v[98:99], v96, off
.LBB0_379:
	s_or_b64 exec, exec, s[24:25]
	v_lshlrev_b32_e32 v96, 16, v140
	s_waitcnt lgkmcnt(0)
	v_and_b32_e32 v97, 0xffff0000, v140
	v_lshlrev_b32_e32 v98, 16, v141
	v_and_b32_e32 v99, 0xffff0000, v141
	v_lshlrev_b32_e32 v100, 16, v142
	v_and_b32_e32 v101, 0xffff0000, v142
	v_pk_fma_f32 v[92:93], v[92:93], 0.5, v[96:97] op_sel_hi:[1,0,1]
	v_pk_fma_f32 v[94:95], v[94:95], 0.5, v[98:99] op_sel_hi:[1,0,1]
	v_pk_fma_f32 v[98:99], v[88:89], 0.5, v[100:101] op_sel_hi:[1,0,1]
	v_cvt_pk_bf16_f32 v88, v92, v93
	v_mul_f32_e32 v93, v93, v93
	v_lshlrev_b32_e32 v102, 16, v143
	v_and_b32_e32 v103, 0xffff0000, v143
	v_fmac_f32_e32 v93, v92, v92
	v_mul_f32_e32 v92, v95, v95
	v_pk_fma_f32 v[96:97], v[90:91], 0.5, v[102:103] op_sel_hi:[1,0,1]
	v_fmac_f32_e32 v92, v94, v94
	v_cvt_pk_bf16_f32 v89, v94, v95
	v_add_f32_e32 v92, v93, v92
	v_mul_f32_e32 v93, v99, v99
	v_mul_f32_e32 v94, v97, v97
	v_fmac_f32_e32 v93, v98, v98
	v_fmac_f32_e32 v94, v96, v96
	v_add_f32_e32 v93, v93, v94
	v_add_f32_e32 v100, v92, v93
	v_lshlrev_b32_e32 v92, 16, v136
	v_and_b32_e32 v93, 0xffff0000, v136
	v_lshlrev_b32_e32 v94, 16, v137
	v_and_b32_e32 v95, 0xffff0000, v137
	v_cvt_pk_bf16_f32 v90, v98, v99
	v_cvt_pk_bf16_f32 v91, v96, v97
	v_lshlrev_b32_e32 v96, 16, v138
	v_and_b32_e32 v97, 0xffff0000, v138
	v_pk_fma_f32 v[86:87], v[86:87], 0.5, v[94:95] op_sel_hi:[1,0,1]
	v_pk_fma_f32 v[84:85], v[84:85], 0.5, v[92:93] op_sel_hi:[1,0,1]
	v_lshlrev_b32_e32 v98, 16, v139
	v_and_b32_e32 v99, 0xffff0000, v139
	v_pk_fma_f32 v[94:95], v[80:81], 0.5, v[96:97] op_sel_hi:[1,0,1]
	v_mul_f32_e32 v80, v85, v85
	v_mul_f32_e32 v81, v87, v87
	v_pk_fma_f32 v[92:93], v[82:83], 0.5, v[98:99] op_sel_hi:[1,0,1]
	v_fmac_f32_e32 v80, v84, v84
	v_fmac_f32_e32 v81, v86, v86
	v_add_f32_e32 v80, v80, v81
	v_mul_f32_e32 v81, v95, v95
	v_mul_f32_e32 v82, v93, v93
	v_fmac_f32_e32 v81, v94, v94
	v_fmac_f32_e32 v82, v92, v92
	v_add_f32_e32 v81, v81, v82
	v_add_f32_e32 v80, v80, v81
	v_add_f32_e32 v83, v100, v80
	v_mov_b32_e32 v98, v83
	s_nop 1
	v_permlane16_swap_b32_e32 v83, v98
	v_lshl_add_u64 v[80:81], s[76:77], 0, v[196:197]
	v_lshl_add_u64 v[96:97], v[184:185], 1, v[80:81]
	global_store_dwordx4 v[96:97], v[88:91], off
	v_cvt_pk_bf16_f32 v82, v84, v85
	s_waitcnt lgkmcnt(0)
	v_add_f32_e32 v80, v83, v98
	v_mov_b32_e32 v81, v80
	s_nop 1
	v_permlane32_swap_b32_e32 v80, v81
	v_cvt_pk_bf16_f32 v83, v86, v87
	v_cvt_pk_bf16_f32 v84, v94, v95
	v_cvt_pk_bf16_f32 v85, v92, v93
	global_store_dwordx4 v[96:97], v[82:85], off offset:256
	s_and_saveexec_b64 s[24:25], s[8:9]
	s_cbranch_execz .LBB0_381
	v_lshlrev_b64 v[82:83], 6, v[194:195]
	v_lshl_add_u64 v[82:83], s[14:15], 0, v[82:83]
	v_lshl_add_u64 v[82:83], s[20:21], 2, v[82:83]
	s_lshl_b32 s4, s34, 2
	v_lshl_add_u64 v[82:83], v[82:83], 0, s[4:5]
	s_waitcnt lgkmcnt(0)
	v_add_f32_e32 v80, v80, v81
	global_store_dword v[82:83], v80, off
; __device__ __forceinline__ unsigned cvt_pk_bf16(float lo, float hi) { unsigned r; asm volatile("v_cvt_pk_bf16_f32 %0, %1, %2" : "=v"(r) : "v"(lo), "v"(hi)); return r; }
;     __device__ __forceinline__ void operator()(const f32x4 (&acc)[2][2][4][2], const Unit& u, int wr, int wc, int fr, int fq) const {
;     ...
;                     for (int bj = 0; bj < 2; ++bj) xin[0][m][bj] = *(const u32x4*)(xb + (size_t)(row0 + ai * HALF + m * 16) * DM + col0 + bj * HALF);
;         }
; #pragma unroll
;             for (int m = 0; m < 4; ++m) {
;                 const int row = row0 + ai * HALF + m * 16; const size_t off = (size_t)row * DM + col0; float q = 0.f;
; #pragma unroll
;                 for (int bj = 0; bj < 2; ++bj) {
;                     const size_t o2 = off + bj * HALF; f32x4 b0, b1;
;                     if (XI_BF16) bf8_to_f32(xin[0][m][bj], b0, b1); else { b0 = *(const f32x4*)(xi + o2); b1 = *(const f32x4*)(xi + o2 + 4); }
;                     const f32x4 o0 = b0 + acc[ai][bj][m][0] * scale, o1 = b1 + acc[ai][bj][m][1] * scale;
;                     u32x4 w; w.x = cvt_pk_bf16(o0[0], o0[1]); w.y = cvt_pk_bf16(o0[2], o0[3]); w.z = cvt_pk_bf16(o1[0], o1[1]); w.w = cvt_pk_bf16(o1[2], o1[3]);
;                     *(u32x4*)(xb + o2) = w;
;                     q += ((o0[0] * o0[0] + o0[1] * o0[1]) + (o0[2] * o0[2] + o0[3] * o0[3])) + ((o1[0] * o1[0] + o1[1] * o1[1]) + (o1[2] * o1[2] + o1[3] * o1[3]));
;                 }
;                 q += __shfl_xor(q, 16); q += __shfl_xor(q, 32);
;                 if (fq == 0) ssout[(size_t)row * 16 + u.pn * 4 + wc] = q;
.LBB0_381:
	s_or_b64 exec, exec, s[24:25]
	v_lshlrev_b32_e32 v80, 16, v132
	s_waitcnt lgkmcnt(0)
	v_and_b32_e32 v81, 0xffff0000, v132
	v_lshlrev_b32_e32 v82, 16, v133
	v_and_b32_e32 v83, 0xffff0000, v133
	v_lshlrev_b32_e32 v84, 16, v134
	v_and_b32_e32 v85, 0xffff0000, v134
	v_pk_fma_f32 v[76:77], v[76:77], 0.5, v[80:81] op_sel_hi:[1,0,1]
	v_pk_fma_f32 v[78:79], v[78:79], 0.5, v[82:83] op_sel_hi:[1,0,1]
	v_pk_fma_f32 v[82:83], v[72:73], 0.5, v[84:85] op_sel_hi:[1,0,1]
	v_cvt_pk_bf16_f32 v72, v76, v77
	v_mul_f32_e32 v77, v77, v77
	v_lshlrev_b32_e32 v86, 16, v135
	v_and_b32_e32 v87, 0xffff0000, v135
	v_fmac_f32_e32 v77, v76, v76
	v_mul_f32_e32 v76, v79, v79
	v_pk_fma_f32 v[80:81], v[74:75], 0.5, v[86:87] op_sel_hi:[1,0,1]
	v_fmac_f32_e32 v76, v78, v78
	v_cvt_pk_bf16_f32 v73, v78, v79
	v_add_f32_e32 v76, v77, v76
	v_mul_f32_e32 v77, v83, v83
	v_mul_f32_e32 v78, v81, v81
	v_fmac_f32_e32 v77, v82, v82
	v_fmac_f32_e32 v78, v80, v80
	v_add_f32_e32 v77, v77, v78
	v_add_f32_e32 v84, v76, v77
	v_lshlrev_b32_e32 v76, 16, v128
	v_and_b32_e32 v77, 0xffff0000, v128
	v_lshlrev_b32_e32 v78, 16, v129
	v_and_b32_e32 v79, 0xffff0000, v129
	v_cvt_pk_bf16_f32 v74, v82, v83
	v_cvt_pk_bf16_f32 v75, v80, v81
	v_lshlrev_b32_e32 v80, 16, v130
	v_and_b32_e32 v81, 0xffff0000, v130
	v_pk_fma_f32 v[70:71], v[70:71], 0.5, v[78:79] op_sel_hi:[1,0,1]
	v_pk_fma_f32 v[68:69], v[68:69], 0.5, v[76:77] op_sel_hi:[1,0,1]
	v_lshlrev_b32_e32 v82, 16, v131
	v_and_b32_e32 v83, 0xffff0000, v131
	v_pk_fma_f32 v[78:79], v[64:65], 0.5, v[80:81] op_sel_hi:[1,0,1]
	v_mul_f32_e32 v64, v69, v69
	v_mul_f32_e32 v65, v71, v71
	v_pk_fma_f32 v[76:77], v[66:67], 0.5, v[82:83] op_sel_hi:[1,0,1]
	v_fmac_f32_e32 v64, v68, v68
	v_fmac_f32_e32 v65, v70, v70
	v_add_f32_e32 v64, v64, v65
	v_mul_f32_e32 v65, v79, v79
	v_mul_f32_e32 v66, v77, v77
	v_fmac_f32_e32 v65, v78, v78
	v_fmac_f32_e32 v66, v76, v76
	v_add_f32_e32 v65, v65, v66
	v_add_f32_e32 v64, v64, v65
	v_add_f32_e32 v67, v84, v64
	v_mov_b32_e32 v82, v67
	s_nop 1
	v_permlane16_swap_b32_e32 v67, v82
	v_lshl_add_u64 v[64:65], s[76:77], 0, v[192:193]
	v_lshl_add_u64 v[80:81], v[184:185], 1, v[64:65]
	global_store_dwordx4 v[80:81], v[72:75], off
	v_cvt_pk_bf16_f32 v66, v68, v69
	s_waitcnt lgkmcnt(0)
	v_add_f32_e32 v64, v67, v82
	v_mov_b32_e32 v65, v64
	s_nop 1
	v_permlane32_swap_b32_e32 v64, v65
	v_cvt_pk_bf16_f32 v67, v70, v71
	v_cvt_pk_bf16_f32 v68, v78, v79
	v_cvt_pk_bf16_f32 v69, v76, v77
	global_store_dwordx4 v[80:81], v[66:69], off offset:256
	s_and_saveexec_b64 s[24:25], s[8:9]
	s_cbranch_execz .LBB0_383
	v_lshlrev_b64 v[66:67], 6, v[190:191]
	v_lshl_add_u64 v[66:67], s[14:15], 0, v[66:67]
	v_lshl_add_u64 v[66:67], s[20:21], 2, v[66:67]
	s_lshl_b32 s4, s34, 2
	v_lshl_add_u64 v[66:67], v[66:67], 0, s[4:5]
	s_waitcnt lgkmcnt(0)
	v_add_f32_e32 v64, v64, v65
	global_store_dword v[66:67], v64, off
.LBB0_383:
	s_or_b64 exec, exec, s[24:25]
	v_add_u32_e32 v100, 0x80, v188
	v_ashrrev_i32_e32 v101, 31, v100
	v_lshlrev_b64 v[110:111], 11, v[100:101]
	s_waitcnt lgkmcnt(0)
	v_lshl_add_u64 v[64:65], v[186:187], 0, v[110:111]
	global_load_dwordx4 v[102:105], v[64:65], off
	global_load_dwordx4 v[106:109], v[64:65], off offset:256
	v_add_u32_e32 v96, 0x90, v188
	v_add_u32_e32 v92, 0xa0, v188
	v_add_u32_e32 v88, 0xb0, v188
	v_ashrrev_i32_e32 v97, 31, v96
	v_ashrrev_i32_e32 v93, 31, v92
	v_ashrrev_i32_e32 v89, 31, v88
	v_lshlrev_b64 v[98:99], 11, v[96:97]
	v_lshlrev_b64 v[94:95], 11, v[92:93]
	v_lshlrev_b64 v[90:91], 11, v[88:89]
	v_lshl_add_u64 v[64:65], v[186:187], 0, v[98:99]
	v_lshl_add_u64 v[66:67], v[186:187], 0, v[94:95]
	v_lshl_add_u64 v[114:115], v[186:187], 0, v[90:91]
	global_load_dwordx4 v[84:87], v[64:65], off
	global_load_dwordx4 v[80:83], v[64:65], off offset:256
	global_load_dwordx4 v[76:79], v[66:67], off
	global_load_dwordx4 v[72:75], v[66:67], off offset:256
	global_load_dwordx4 v[68:71], v[114:115], off
	s_nop 0
	global_load_dwordx4 v[64:67], v[114:115], off offset:256
	s_waitcnt vmcnt(7)
	v_lshlrev_b32_e32 v114, 16, v102
	v_and_b32_e32 v115, 0xffff0000, v102
	v_lshlrev_b32_e32 v102, 16, v103
	v_and_b32_e32 v103, 0xffff0000, v103
	v_lshlrev_b32_e32 v116, 16, v104
	v_and_b32_e32 v117, 0xffff0000, v104
	v_lshlrev_b32_e32 v104, 16, v105
	v_and_b32_e32 v105, 0xffff0000, v105
	s_waitcnt vmcnt(6)
	v_lshlrev_b32_e32 v118, 16, v106
	v_and_b32_e32 v119, 0xffff0000, v106
	v_lshlrev_b32_e32 v106, 16, v107
	v_and_b32_e32 v107, 0xffff0000, v107
	v_lshlrev_b32_e32 v120, 16, v108
	v_and_b32_e32 v121, 0xffff0000, v108
	v_lshlrev_b32_e32 v108, 16, v109
	v_and_b32_e32 v109, 0xffff0000, v109
	v_pk_fma_f32 v[62:63], v[62:63], 0.5, v[102:103] op_sel_hi:[1,0,1]
	v_pk_fma_f32 v[60:61], v[60:61], 0.5, v[114:115] op_sel_hi:[1,0,1]
	v_pk_fma_f32 v[58:59], v[58:59], 0.5, v[104:105] op_sel_hi:[1,0,1]
	v_pk_fma_f32 v[56:57], v[56:57], 0.5, v[116:117] op_sel_hi:[1,0,1]
	v_pk_fma_f32 v[54:55], v[54:55], 0.5, v[106:107] op_sel_hi:[1,0,1]
	v_pk_fma_f32 v[52:53], v[52:53], 0.5, v[118:119] op_sel_hi:[1,0,1]
	v_pk_fma_f32 v[102:103], v[50:51], 0.5, v[108:109] op_sel_hi:[1,0,1]
	v_pk_fma_f32 v[104:105], v[48:49], 0.5, v[120:121] op_sel_hi:[1,0,1]
	v_cvt_pk_bf16_f32 v48, v60, v61
	v_cvt_pk_bf16_f32 v49, v62, v63
	v_cvt_pk_bf16_f32 v50, v56, v57
	v_cvt_pk_bf16_f32 v51, v58, v59
	v_mul_f32_e32 v61, v61, v61
	v_mul_f32_e32 v63, v63, v63
	v_mul_f32_e32 v57, v57, v57
	v_mul_f32_e32 v59, v59, v59
	v_mul_f32_e32 v106, v53, v53
	v_mul_f32_e32 v107, v55, v55
	v_mul_f32_e32 v108, v105, v105
	v_mul_f32_e32 v109, v103, v103
	v_fmac_f32_e32 v61, v60, v60
	v_fmac_f32_e32 v63, v62, v62
	v_fmac_f32_e32 v57, v56, v56
	v_fmac_f32_e32 v59, v58, v58
	v_fmac_f32_e32 v106, v52, v52
	v_fmac_f32_e32 v107, v54, v54
	v_fmac_f32_e32 v108, v104, v104
	v_fmac_f32_e32 v109, v102, v102
	v_add_f32_e32 v56, v61, v63
	v_add_f32_e32 v57, v57, v59
	v_add_f32_e32 v58, v106, v107
	v_add_f32_e32 v59, v108, v109
	v_add_f32_e32 v56, v56, v57
	v_add_f32_e32 v57, v58, v59
	v_add_f32_e32 v58, v56, v57
	v_mov_b32_e32 v59, v58
	s_nop 1
	v_permlane16_swap_b32_e32 v58, v59
	v_lshl_add_u64 v[56:57], s[76:77], 0, v[110:111]
	v_lshl_add_u64 v[56:57], v[184:185], 1, v[56:57]
	global_store_dwordx4 v[56:57], v[48:51], off
	s_waitcnt lgkmcnt(0)
	s_nop 0
	v_add_f32_e32 v48, v58, v59
	v_mov_b32_e32 v49, v48
	s_nop 1
	v_permlane32_swap_b32_e32 v48, v49
	v_cvt_pk_bf16_f32 v50, v52, v53
	v_cvt_pk_bf16_f32 v51, v54, v55
	v_cvt_pk_bf16_f32 v52, v104, v105
	v_cvt_pk_bf16_f32 v53, v102, v103
	global_store_dwordx4 v[56:57], v[50:53], off offset:256
	s_and_saveexec_b64 s[24:25], s[8:9]
	s_cbranch_execz .LBB0_385
	v_lshlrev_b64 v[50:51], 6, v[100:101]
	v_lshl_add_u64 v[50:51], s[14:15], 0, v[50:51]
	v_lshl_add_u64 v[50:51], s[20:21], 2, v[50:51]
	s_lshl_b32 s4, s34, 2
	v_lshl_add_u64 v[50:51], v[50:51], 0, s[4:5]
	s_waitcnt lgkmcnt(0)
	v_add_f32_e32 v48, v48, v49
	global_store_dword v[50:51], v48, off
; __device__ __forceinline__ unsigned cvt_pk_bf16(float lo, float hi) { unsigned r; asm volatile("v_cvt_pk_bf16_f32 %0, %1, %2" : "=v"(r) : "v"(lo), "v"(hi)); return r; }
;     __device__ __forceinline__ void operator()(const f32x4 (&acc)[2][2][4][2], const Unit& u, int wr, int wc, int fr, int fq) const {
;     ...
; #pragma unroll
;             for (int m = 0; m < 4; ++m) {
;                 const int row = row0 + ai * HALF + m * 16; const size_t off = (size_t)row * DM + col0; float q = 0.f;
; #pragma unroll
;                 for (int bj = 0; bj < 2; ++bj) {
;                     const size_t o2 = off + bj * HALF; f32x4 b0, b1;
;                     if (XI_BF16) bf8_to_f32(xin[0][m][bj], b0, b1); else { b0 = *(const f32x4*)(xi + o2); b1 = *(const f32x4*)(xi + o2 + 4); }
;                     const f32x4 o0 = b0 + acc[ai][bj][m][0] * scale, o1 = b1 + acc[ai][bj][m][1] * scale;
;                     u32x4 w; w.x = cvt_pk_bf16(o0[0], o0[1]); w.y = cvt_pk_bf16(o0[2], o0[3]); w.z = cvt_pk_bf16(o1[0], o1[1]); w.w = cvt_pk_bf16(o1[2], o1[3]);
;                     *(u32x4*)(xb + o2) = w;
;                     q += ((o0[0] * o0[0] + o0[1] * o0[1]) + (o0[2] * o0[2] + o0[3] * o0[3])) + ((o1[0] * o1[0] + o1[1] * o1[1]) + (o1[2] * o1[2] + o1[3] * o1[3]));
;                 }
;                 q += __shfl_xor(q, 16); q += __shfl_xor(q, 32);
;                 if (fq == 0) ssout[(size_t)row * 16 + u.pn * 4 + wc] = q;
.LBB0_385:
	s_or_b64 exec, exec, s[24:25]
	s_waitcnt vmcnt(7)
	v_lshlrev_b32_e32 v48, 16, v84
	s_waitcnt lgkmcnt(0)
	v_and_b32_e32 v49, 0xffff0000, v84
	v_lshlrev_b32_e32 v50, 16, v85
	v_and_b32_e32 v51, 0xffff0000, v85
	v_lshlrev_b32_e32 v52, 16, v86
	v_and_b32_e32 v53, 0xffff0000, v86
	v_pk_fma_f32 v[44:45], v[44:45], 0.5, v[48:49] op_sel_hi:[1,0,1]
	v_pk_fma_f32 v[46:47], v[46:47], 0.5, v[50:51] op_sel_hi:[1,0,1]
	v_pk_fma_f32 v[50:51], v[40:41], 0.5, v[52:53] op_sel_hi:[1,0,1]
	v_cvt_pk_bf16_f32 v40, v44, v45
	v_mul_f32_e32 v45, v45, v45
	v_lshlrev_b32_e32 v54, 16, v87
	v_and_b32_e32 v55, 0xffff0000, v87
	v_fmac_f32_e32 v45, v44, v44
	v_mul_f32_e32 v44, v47, v47
	v_pk_fma_f32 v[48:49], v[42:43], 0.5, v[54:55] op_sel_hi:[1,0,1]
	v_fmac_f32_e32 v44, v46, v46
	v_cvt_pk_bf16_f32 v41, v46, v47
	v_add_f32_e32 v44, v45, v44
	v_mul_f32_e32 v45, v51, v51
	v_mul_f32_e32 v46, v49, v49
	v_fmac_f32_e32 v45, v50, v50
	v_fmac_f32_e32 v46, v48, v48
	v_add_f32_e32 v45, v45, v46
	v_add_f32_e32 v52, v44, v45
	s_waitcnt vmcnt(6)
	v_lshlrev_b32_e32 v44, 16, v80
	v_and_b32_e32 v45, 0xffff0000, v80
	v_lshlrev_b32_e32 v46, 16, v81
	v_and_b32_e32 v47, 0xffff0000, v81
	v_cvt_pk_bf16_f32 v42, v50, v51
	v_cvt_pk_bf16_f32 v43, v48, v49
	v_lshlrev_b32_e32 v48, 16, v82
	v_and_b32_e32 v49, 0xffff0000, v82
	v_pk_fma_f32 v[38:39], v[38:39], 0.5, v[46:47] op_sel_hi:[1,0,1]
	v_pk_fma_f32 v[36:37], v[36:37], 0.5, v[44:45] op_sel_hi:[1,0,1]
	v_lshlrev_b32_e32 v50, 16, v83
	v_and_b32_e32 v51, 0xffff0000, v83
	v_pk_fma_f32 v[46:47], v[32:33], 0.5, v[48:49] op_sel_hi:[1,0,1]
	v_mul_f32_e32 v32, v37, v37
	v_mul_f32_e32 v33, v39, v39
	v_pk_fma_f32 v[44:45], v[34:35], 0.5, v[50:51] op_sel_hi:[1,0,1]
	v_fmac_f32_e32 v32, v36, v36
	v_fmac_f32_e32 v33, v38, v38
	v_add_f32_e32 v32, v32, v33
	v_mul_f32_e32 v33, v47, v47
	v_mul_f32_e32 v34, v45, v45
	v_fmac_f32_e32 v33, v46, v46
	v_fmac_f32_e32 v34, v44, v44
	v_add_f32_e32 v33, v33, v34
	v_add_f32_e32 v32, v32, v33
	v_add_f32_e32 v35, v52, v32
	v_mov_b32_e32 v50, v35
	s_nop 1
	v_permlane16_swap_b32_e32 v35, v50
	v_lshl_add_u64 v[32:33], s[76:77], 0, v[98:99]
	v_lshl_add_u64 v[48:49], v[184:185], 1, v[32:33]
	global_store_dwordx4 v[48:49], v[40:43], off
	v_cvt_pk_bf16_f32 v34, v36, v37
	s_waitcnt lgkmcnt(0)
	v_add_f32_e32 v32, v35, v50
	v_mov_b32_e32 v33, v32
	s_nop 1
	v_permlane32_swap_b32_e32 v32, v33
	v_cvt_pk_bf16_f32 v35, v38, v39
	v_cvt_pk_bf16_f32 v36, v46, v47
	v_cvt_pk_bf16_f32 v37, v44, v45
	global_store_dwordx4 v[48:49], v[34:37], off offset:256
	s_and_saveexec_b64 s[24:25], s[8:9]
	s_cbranch_execz .LBB0_387
	v_lshlrev_b64 v[34:35], 6, v[96:97]
	v_lshl_add_u64 v[34:35], s[14:15], 0, v[34:35]
	v_lshl_add_u64 v[34:35], s[20:21], 2, v[34:35]
	s_lshl_b32 s4, s34, 2
	v_lshl_add_u64 v[34:35], v[34:35], 0, s[4:5]
	s_waitcnt lgkmcnt(0)
	v_add_f32_e32 v32, v32, v33
	global_store_dword v[34:35], v32, off
; __device__ __forceinline__ unsigned cvt_pk_bf16(float lo, float hi) { unsigned r; asm volatile("v_cvt_pk_bf16_f32 %0, %1, %2" : "=v"(r) : "v"(lo), "v"(hi)); return r; }
;     __device__ __forceinline__ void operator()(const f32x4 (&acc)[2][2][4][2], const Unit& u, int wr, int wc, int fr, int fq) const {
;     ...
; #pragma unroll
;             for (int m = 0; m < 4; ++m) {
;                 const int row = row0 + ai * HALF + m * 16; const size_t off = (size_t)row * DM + col0; float q = 0.f;
; #pragma unroll
;                 for (int bj = 0; bj < 2; ++bj) {
;                     const size_t o2 = off + bj * HALF; f32x4 b0, b1;
;                     if (XI_BF16) bf8_to_f32(xin[0][m][bj], b0, b1); else { b0 = *(const f32x4*)(xi + o2); b1 = *(const f32x4*)(xi + o2 + 4); }
;                     const f32x4 o0 = b0 + acc[ai][bj][m][0] * scale, o1 = b1 + acc[ai][bj][m][1] * scale;
;                     u32x4 w; w.x = cvt_pk_bf16(o0[0], o0[1]); w.y = cvt_pk_bf16(o0[2], o0[3]); w.z = cvt_pk_bf16(o1[0], o1[1]); w.w = cvt_pk_bf16(o1[2], o1[3]);
;                     *(u32x4*)(xb + o2) = w;
;                     q += ((o0[0] * o0[0] + o0[1] * o0[1]) + (o0[2] * o0[2] + o0[3] * o0[3])) + ((o1[0] * o1[0] + o1[1] * o1[1]) + (o1[2] * o1[2] + o1[3] * o1[3]));
;                 }
;                 q += __shfl_xor(q, 16); q += __shfl_xor(q, 32);
;                 if (fq == 0) ssout[(size_t)row * 16 + u.pn * 4 + wc] = q;
.LBB0_387:
	s_or_b64 exec, exec, s[24:25]
	s_waitcnt vmcnt(7)
	v_lshlrev_b32_e32 v32, 16, v76
	s_waitcnt lgkmcnt(0)
	v_and_b32_e32 v33, 0xffff0000, v76
	v_lshlrev_b32_e32 v34, 16, v77
	v_and_b32_e32 v35, 0xffff0000, v77
	v_lshlrev_b32_e32 v36, 16, v78
	v_and_b32_e32 v37, 0xffff0000, v78
	v_pk_fma_f32 v[28:29], v[28:29], 0.5, v[32:33] op_sel_hi:[1,0,1]
	v_pk_fma_f32 v[30:31], v[30:31], 0.5, v[34:35] op_sel_hi:[1,0,1]
	v_pk_fma_f32 v[34:35], v[24:25], 0.5, v[36:37] op_sel_hi:[1,0,1]
	v_cvt_pk_bf16_f32 v24, v28, v29
	v_mul_f32_e32 v29, v29, v29
	v_lshlrev_b32_e32 v38, 16, v79
	v_and_b32_e32 v39, 0xffff0000, v79
	v_fmac_f32_e32 v29, v28, v28
	v_mul_f32_e32 v28, v31, v31
	v_pk_fma_f32 v[32:33], v[26:27], 0.5, v[38:39] op_sel_hi:[1,0,1]
	v_fmac_f32_e32 v28, v30, v30
	v_cvt_pk_bf16_f32 v25, v30, v31
	v_add_f32_e32 v28, v29, v28
	v_mul_f32_e32 v29, v35, v35
	v_mul_f32_e32 v30, v33, v33
	v_fmac_f32_e32 v29, v34, v34
	v_fmac_f32_e32 v30, v32, v32
	v_add_f32_e32 v29, v29, v30
	v_add_f32_e32 v36, v28, v29
	s_waitcnt vmcnt(6)
	v_lshlrev_b32_e32 v28, 16, v72
	v_and_b32_e32 v29, 0xffff0000, v72
	v_lshlrev_b32_e32 v30, 16, v73
	v_and_b32_e32 v31, 0xffff0000, v73
	v_cvt_pk_bf16_f32 v26, v34, v35
	v_cvt_pk_bf16_f32 v27, v32, v33
	v_lshlrev_b32_e32 v32, 16, v74
	v_and_b32_e32 v33, 0xffff0000, v74
	v_pk_fma_f32 v[22:23], v[22:23], 0.5, v[30:31] op_sel_hi:[1,0,1]
	v_pk_fma_f32 v[20:21], v[20:21], 0.5, v[28:29] op_sel_hi:[1,0,1]
	v_lshlrev_b32_e32 v34, 16, v75
	v_and_b32_e32 v35, 0xffff0000, v75
	v_pk_fma_f32 v[30:31], v[16:17], 0.5, v[32:33] op_sel_hi:[1,0,1]
	v_mul_f32_e32 v16, v21, v21
	v_mul_f32_e32 v17, v23, v23
	v_pk_fma_f32 v[28:29], v[18:19], 0.5, v[34:35] op_sel_hi:[1,0,1]
	v_fmac_f32_e32 v16, v20, v20
	v_fmac_f32_e32 v17, v22, v22
	v_add_f32_e32 v16, v16, v17
	v_mul_f32_e32 v17, v31, v31
	v_mul_f32_e32 v18, v29, v29
	v_fmac_f32_e32 v17, v30, v30
	v_fmac_f32_e32 v18, v28, v28
	v_add_f32_e32 v17, v17, v18
	v_add_f32_e32 v16, v16, v17
	v_add_f32_e32 v19, v36, v16
	v_mov_b32_e32 v34, v19
	s_nop 1
	v_permlane16_swap_b32_e32 v19, v34
	v_lshl_add_u64 v[16:17], s[76:77], 0, v[94:95]
	v_lshl_add_u64 v[32:33], v[184:185], 1, v[16:17]
	global_store_dwordx4 v[32:33], v[24:27], off
	v_cvt_pk_bf16_f32 v18, v20, v21
	s_waitcnt lgkmcnt(0)
	v_add_f32_e32 v16, v19, v34
	v_mov_b32_e32 v17, v16
	s_nop 1
	v_permlane32_swap_b32_e32 v16, v17
	v_cvt_pk_bf16_f32 v19, v22, v23
	v_cvt_pk_bf16_f32 v20, v30, v31
	v_cvt_pk_bf16_f32 v21, v28, v29
	global_store_dwordx4 v[32:33], v[18:21], off offset:256
	s_and_saveexec_b64 s[24:25], s[8:9]
	s_cbranch_execz .LBB0_389
	v_lshlrev_b64 v[18:19], 6, v[92:93]
	v_lshl_add_u64 v[18:19], s[14:15], 0, v[18:19]
	v_lshl_add_u64 v[18:19], s[20:21], 2, v[18:19]
	s_lshl_b32 s4, s34, 2
	v_lshl_add_u64 v[18:19], v[18:19], 0, s[4:5]
	s_waitcnt lgkmcnt(0)
	v_add_f32_e32 v16, v16, v17
	global_store_dword v[18:19], v16, off
.LBB0_389:
	s_or_b64 exec, exec, s[24:25]
	s_waitcnt vmcnt(7)
	v_lshlrev_b32_e32 v16, 16, v68
	s_waitcnt lgkmcnt(0)
	v_and_b32_e32 v17, 0xffff0000, v68
	v_lshlrev_b32_e32 v18, 16, v69
	v_and_b32_e32 v19, 0xffff0000, v69
	v_lshlrev_b32_e32 v20, 16, v70
	v_and_b32_e32 v21, 0xffff0000, v70
	v_pk_fma_f32 v[12:13], v[12:13], 0.5, v[16:17] op_sel_hi:[1,0,1]
	v_pk_fma_f32 v[14:15], v[14:15], 0.5, v[18:19] op_sel_hi:[1,0,1]
	v_pk_fma_f32 v[18:19], v[8:9], 0.5, v[20:21] op_sel_hi:[1,0,1]
	v_cvt_pk_bf16_f32 v8, v12, v13
	v_mul_f32_e32 v13, v13, v13
	v_lshlrev_b32_e32 v22, 16, v71
	v_and_b32_e32 v23, 0xffff0000, v71
	v_fmac_f32_e32 v13, v12, v12
	v_mul_f32_e32 v12, v15, v15
	v_pk_fma_f32 v[16:17], v[10:11], 0.5, v[22:23] op_sel_hi:[1,0,1]
	v_fmac_f32_e32 v12, v14, v14
	v_cvt_pk_bf16_f32 v9, v14, v15
	v_add_f32_e32 v12, v13, v12
	v_mul_f32_e32 v13, v19, v19
	v_mul_f32_e32 v14, v17, v17
	v_fmac_f32_e32 v13, v18, v18
	v_fmac_f32_e32 v14, v16, v16
	v_add_f32_e32 v13, v13, v14
	v_add_f32_e32 v20, v12, v13
	s_waitcnt vmcnt(6)
	v_lshlrev_b32_e32 v12, 16, v64
	v_and_b32_e32 v13, 0xffff0000, v64
	v_lshlrev_b32_e32 v14, 16, v65
	v_and_b32_e32 v15, 0xffff0000, v65
	v_cvt_pk_bf16_f32 v10, v18, v19
	v_cvt_pk_bf16_f32 v11, v16, v17
	v_lshlrev_b32_e32 v16, 16, v66
	v_and_b32_e32 v17, 0xffff0000, v66
	v_pk_fma_f32 v[6:7], v[6:7], 0.5, v[14:15] op_sel_hi:[1,0,1]
	v_pk_fma_f32 v[4:5], v[4:5], 0.5, v[12:13] op_sel_hi:[1,0,1]
	v_lshlrev_b32_e32 v18, 16, v67
	v_and_b32_e32 v19, 0xffff0000, v67
	v_pk_fma_f32 v[14:15], v[0:1], 0.5, v[16:17] op_sel_hi:[1,0,1]
	v_mul_f32_e32 v0, v5, v5
	v_mul_f32_e32 v1, v7, v7
	v_pk_fma_f32 v[12:13], v[2:3], 0.5, v[18:19] op_sel_hi:[1,0,1]
	v_fmac_f32_e32 v0, v4, v4
	v_fmac_f32_e32 v1, v6, v6
	v_add_f32_e32 v0, v0, v1
	v_mul_f32_e32 v1, v15, v15
	v_mul_f32_e32 v2, v13, v13
	v_fmac_f32_e32 v1, v14, v14
	v_fmac_f32_e32 v2, v12, v12
	v_add_f32_e32 v1, v1, v2
	v_add_f32_e32 v0, v0, v1
	v_add_f32_e32 v3, v20, v0
	v_mov_b32_e32 v18, v3
	s_nop 1
	v_permlane16_swap_b32_e32 v3, v18
	v_lshl_add_u64 v[0:1], s[76:77], 0, v[90:91]
	v_lshl_add_u64 v[16:17], v[184:185], 1, v[0:1]
	global_store_dwordx4 v[16:17], v[8:11], off
	v_cvt_pk_bf16_f32 v2, v4, v5
	s_waitcnt lgkmcnt(0)
	v_add_f32_e32 v0, v3, v18
	v_mov_b32_e32 v1, v0
	s_nop 1
	v_permlane32_swap_b32_e32 v0, v1
	v_cvt_pk_bf16_f32 v3, v6, v7
	v_cvt_pk_bf16_f32 v4, v14, v15
	v_cvt_pk_bf16_f32 v5, v12, v13
	global_store_dwordx4 v[16:17], v[2:5], off offset:256
	s_and_saveexec_b64 s[24:25], s[8:9]
	s_cbranch_execz .LBB0_391
	v_lshlrev_b64 v[2:3], 6, v[88:89]
	v_lshl_add_u64 v[2:3], s[14:15], 0, v[2:3]
	v_lshl_add_u64 v[2:3], s[20:21], 2, v[2:3]
	s_lshl_b32 s4, s34, 2
	v_lshl_add_u64 v[2:3], v[2:3], 0, s[4:5]
	s_waitcnt lgkmcnt(0)
	v_add_f32_e32 v0, v0, v1
	global_store_dword v[2:3], v0, off

; __device__ __forceinline__ unsigned cvt_pk_bf16(float lo, float hi) { unsigned r; asm volatile("v_cvt_pk_bf16_f32 %0, %1, %2" : "=v"(r) : "v"(lo), "v"(hi)); return r; }
;     __device__ __forceinline__ void operator()(const f32x4 (&acc)[2][2][4][2], const Unit& u, int wr, int wc, int fr, int fq) const {
;     ...
;                     for (int bj = 0; bj < 2; ++bj) xin[0][m][bj] = *(const u32x4*)(xb + (size_t)(row0 + ai * HALF + m * 16) * DM + col0 + bj * HALF);
;         }
; #pragma unroll
;             for (int m = 0; m < 4; ++m) {
;                 const int row = row0 + ai * HALF + m * 16; const size_t off = (size_t)row * DM + col0; float q = 0.f;
; #pragma unroll
;                 for (int bj = 0; bj < 2; ++bj) {
;                     const size_t o2 = off + bj * HALF; f32x4 b0, b1;
;                     if (XI_BF16) bf8_to_f32(xin[0][m][bj], b0, b1); else { b0 = *(const f32x4*)(xi + o2); b1 = *(const f32x4*)(xi + o2 + 4); }
;                     const f32x4 o0 = b0 + acc[ai][bj][m][0] * scale, o1 = b1 + acc[ai][bj][m][1] * scale;
;                     u32x4 w; w.x = cvt_pk_bf16(o0[0], o0[1]); w.y = cvt_pk_bf16(o0[2], o0[3]); w.z = cvt_pk_bf16(o1[0], o1[1]); w.w = cvt_pk_bf16(o1[2], o1[3]);
;                     *(u32x4*)(xb + o2) = w;
;                     q += ((o0[0] * o0[0] + o0[1] * o0[1]) + (o0[2] * o0[2] + o0[3] * o0[3])) + ((o1[0] * o1[0] + o1[1] * o1[1]) + (o1[2] * o1[2] + o1[3] * o1[3]));
;                 }
;                 q += __shfl_xor(q, 16); q += __shfl_xor(q, 32);
;                 if (fq == 0) ssout[(size_t)row * 16 + u.pn * 4 + wc] = q;
.LBB0_1233:
	v_lshl_or_b32 v182, s0, 8, v171
	v_lshl_add_u32 v186, s24, 8, v165
	v_ashrrev_i32_e32 v183, 31, v182
	v_lshlrev_b64 v[214:215], 1, v[182:183]
	v_ashrrev_i32_e32 v187, 31, v186
	v_lshl_add_u64 v[184:185], s[76:77], 0, v[214:215]
	v_lshlrev_b64 v[204:205], 11, v[186:187]
	v_lshl_add_u64 v[128:129], v[184:185], 0, v[204:205]
	global_load_dwordx4 v[206:209], v[128:129], off
	global_load_dwordx4 v[210:213], v[128:129], off offset:256
	v_or_b32_e32 v196, 16, v186
	v_or_b32_e32 v192, 32, v186
	v_or_b32_e32 v188, 48, v186
	v_ashrrev_i32_e32 v197, 31, v196
	v_ashrrev_i32_e32 v193, 31, v192
	v_ashrrev_i32_e32 v189, 31, v188
	v_lshlrev_b64 v[198:199], 11, v[196:197]
	v_lshlrev_b64 v[194:195], 11, v[192:193]
	v_lshlrev_b64 v[190:191], 11, v[188:189]
	v_lshl_add_u64 v[128:129], v[184:185], 0, v[198:199]
	v_lshl_add_u64 v[130:131], v[184:185], 0, v[194:195]
	v_lshl_add_u64 v[216:217], v[184:185], 0, v[190:191]
	global_load_dwordx4 v[148:151], v[128:129], off
	global_load_dwordx4 v[144:147], v[128:129], off offset:256
	global_load_dwordx4 v[140:143], v[130:131], off
	global_load_dwordx4 v[136:139], v[130:131], off offset:256
	global_load_dwordx4 v[132:135], v[216:217], off
	s_nop 0
	global_load_dwordx4 v[128:131], v[216:217], off offset:256
	v_and_b32_e32 v217, 64, v203
	v_xor_b32_e32 v216, 16, v203
	v_add_u32_e32 v217, 64, v217
	v_xor_b32_e32 v218, 32, v203
	v_cmp_lt_i32_e32 vcc, v216, v217
	s_lshl_b32 s24, s0, 2
	s_ashr_i32 s25, s24, 31
	v_cndmask_b32_e32 v219, v203, v216, vcc
	v_cmp_lt_i32_e32 vcc, v218, v217
	v_lshl_add_u64 v[216:217], s[76:77], 0, v[204:205]
	v_lshlrev_b32_e32 v204, 2, v219
	v_cndmask_b32_e32 v224, v203, v218, vcc
	v_lshl_add_u64 v[214:215], v[216:217], 0, v[214:215]
	s_waitcnt vmcnt(0)
	v_lshlrev_b32_e32 v216, 16, v206
	v_and_b32_e32 v217, 0xffff0000, v206
	v_lshlrev_b32_e32 v206, 16, v207
	v_and_b32_e32 v207, 0xffff0000, v207
	v_lshlrev_b32_e32 v218, 16, v208
	v_and_b32_e32 v219, 0xffff0000, v208
	v_lshlrev_b32_e32 v208, 16, v209
	v_and_b32_e32 v209, 0xffff0000, v209
	v_lshlrev_b32_e32 v220, 16, v210
	v_and_b32_e32 v221, 0xffff0000, v210
	v_lshlrev_b32_e32 v210, 16, v211
	v_and_b32_e32 v211, 0xffff0000, v211
	v_lshlrev_b32_e32 v222, 16, v212
	v_and_b32_e32 v223, 0xffff0000, v212
	v_lshlrev_b32_e32 v212, 16, v213
	v_and_b32_e32 v213, 0xffff0000, v213
	v_pk_add_f32 v[126:127], v[126:127], v[206:207]
	v_pk_add_f32 v[124:125], v[124:125], v[216:217]
	v_pk_add_f32 v[122:123], v[122:123], v[208:209]
	v_pk_add_f32 v[120:121], v[120:121], v[218:219]
	v_pk_add_f32 v[118:119], v[118:119], v[210:211]
	v_pk_add_f32 v[116:117], v[116:117], v[220:221]
	v_pk_add_f32 v[206:207], v[114:115], v[212:213]
	v_pk_add_f32 v[208:209], v[112:113], v[222:223]
	v_cvt_pk_bf16_f32 v112, v124, v125
	v_cvt_pk_bf16_f32 v113, v126, v127
	v_mul_f32_e32 v114, v125, v125
	v_mul_f32_e32 v115, v127, v127
	v_mul_f32_e32 v125, v121, v121
	v_mul_f32_e32 v127, v123, v123
	v_mul_f32_e32 v205, v117, v117
	v_mul_f32_e32 v210, v119, v119
	v_mul_f32_e32 v211, v209, v209
	v_mul_f32_e32 v212, v207, v207
	v_fmac_f32_e32 v114, v124, v124
	v_fmac_f32_e32 v115, v126, v126
	v_fmac_f32_e32 v125, v120, v120
	v_fmac_f32_e32 v127, v122, v122
	v_fmac_f32_e32 v205, v116, v116
	v_fmac_f32_e32 v210, v118, v118
	v_fmac_f32_e32 v211, v208, v208
	v_fmac_f32_e32 v212, v206, v206
	v_add_f32_e32 v114, v114, v115
	v_add_f32_e32 v115, v125, v127
	v_add_f32_e32 v124, v205, v210
	v_add_f32_e32 v125, v211, v212
	v_add_f32_e32 v114, v114, v115
	v_add_f32_e32 v115, v124, v125
	v_add_f32_e32 v124, v114, v115
	v_mov_b32_e32 v125, v124
	s_nop 1
	v_permlane16_swap_b32_e32 v124, v125
	v_cvt_pk_bf16_f32 v114, v120, v121
	v_cvt_pk_bf16_f32 v115, v122, v123
	global_store_dwordx4 v[214:215], v[112:115], off
	v_cvt_pk_bf16_f32 v116, v116, v117
	v_cvt_pk_bf16_f32 v117, v118, v119
	v_cvt_pk_bf16_f32 v118, v208, v209
	v_cvt_pk_bf16_f32 v119, v206, v207
	global_store_dwordx4 v[214:215], v[116:119], off offset:256
	s_waitcnt lgkmcnt(0)
	v_add_f32_e32 v113, v124, v125
	v_lshlrev_b32_e32 v112, 2, v224
	v_mov_b32_e32 v114, v113
	s_nop 1
	v_permlane32_swap_b32_e32 v113, v114
	s_and_saveexec_b64 s[26:27], s[8:9]
	s_cbranch_execz .LBB0_1235
	v_lshlrev_b64 v[116:117], 6, v[186:187]
	v_lshl_add_u64 v[116:117], s[12:13], 0, v[116:117]
	v_lshl_add_u64 v[116:117], s[24:25], 2, v[116:117]
	s_lshl_b32 s0, s38, 2
	v_lshl_add_u64 v[116:117], v[116:117], 0, s[0:1]
	s_waitcnt lgkmcnt(0)
	v_add_f32_e32 v113, v113, v114
	global_store_dword v[116:117], v113, off
; __device__ __forceinline__ unsigned cvt_pk_bf16(float lo, float hi) { unsigned r; asm volatile("v_cvt_pk_bf16_f32 %0, %1, %2" : "=v"(r) : "v"(lo), "v"(hi)); return r; }
;     __device__ __forceinline__ void operator()(const f32x4 (&acc)[2][2][4][2], const Unit& u, int wr, int wc, int fr, int fq) const {
;     ...
; #pragma unroll
;             for (int m = 0; m < 4; ++m) {
;                 const int row = row0 + ai * HALF + m * 16; const size_t off = (size_t)row * DM + col0; float q = 0.f;
; #pragma unroll
;                 for (int bj = 0; bj < 2; ++bj) {
;                     const size_t o2 = off + bj * HALF; f32x4 b0, b1;
;                     if (XI_BF16) bf8_to_f32(xin[0][m][bj], b0, b1); else { b0 = *(const f32x4*)(xi + o2); b1 = *(const f32x4*)(xi + o2 + 4); }
;                     const f32x4 o0 = b0 + acc[ai][bj][m][0] * scale, o1 = b1 + acc[ai][bj][m][1] * scale;
;                     u32x4 w; w.x = cvt_pk_bf16(o0[0], o0[1]); w.y = cvt_pk_bf16(o0[2], o0[3]); w.z = cvt_pk_bf16(o1[0], o1[1]); w.w = cvt_pk_bf16(o1[2], o1[3]);
;                     *(u32x4*)(xb + o2) = w;
;                     q += ((o0[0] * o0[0] + o0[1] * o0[1]) + (o0[2] * o0[2] + o0[3] * o0[3])) + ((o1[0] * o1[0] + o1[1] * o1[1]) + (o1[2] * o1[2] + o1[3] * o1[3]));
;                 }
;                 q += __shfl_xor(q, 16); q += __shfl_xor(q, 32);
;                 if (fq == 0) ssout[(size_t)row * 16 + u.pn * 4 + wc] = q;
.LBB0_1235:
	s_or_b64 exec, exec, s[26:27]
	s_waitcnt lgkmcnt(0)
	v_lshlrev_b32_e32 v114, 16, v148
	v_and_b32_e32 v115, 0xffff0000, v148
	v_lshlrev_b32_e32 v116, 16, v149
	v_and_b32_e32 v117, 0xffff0000, v149
	v_lshlrev_b32_e32 v118, 16, v150
	v_and_b32_e32 v119, 0xffff0000, v150
	v_pk_add_f32 v[108:109], v[108:109], v[114:115]
	v_pk_add_f32 v[110:111], v[110:111], v[116:117]
	v_pk_add_f32 v[116:117], v[104:105], v[118:119]
	v_cvt_pk_bf16_f32 v104, v108, v109
	v_mul_f32_e32 v109, v109, v109
	v_lshlrev_b32_e32 v120, 16, v151
	v_and_b32_e32 v121, 0xffff0000, v151
	v_fmac_f32_e32 v109, v108, v108
	v_mul_f32_e32 v108, v111, v111
	v_pk_add_f32 v[114:115], v[106:107], v[120:121]
	v_fmac_f32_e32 v108, v110, v110
	v_cvt_pk_bf16_f32 v105, v110, v111
	v_add_f32_e32 v108, v109, v108
	v_mul_f32_e32 v109, v117, v117
	v_mul_f32_e32 v110, v115, v115
	v_fmac_f32_e32 v109, v116, v116
	v_fmac_f32_e32 v110, v114, v114
	v_add_f32_e32 v109, v109, v110
	v_add_f32_e32 v113, v108, v109
	v_lshlrev_b32_e32 v108, 16, v144
	v_and_b32_e32 v109, 0xffff0000, v144
	v_lshlrev_b32_e32 v110, 16, v145
	v_and_b32_e32 v111, 0xffff0000, v145
	v_cvt_pk_bf16_f32 v106, v116, v117
	v_cvt_pk_bf16_f32 v107, v114, v115
	v_lshlrev_b32_e32 v114, 16, v146
	v_and_b32_e32 v115, 0xffff0000, v146
	v_pk_add_f32 v[102:103], v[102:103], v[110:111]
	v_pk_add_f32 v[100:101], v[100:101], v[108:109]
	v_lshlrev_b32_e32 v116, 16, v147
	v_and_b32_e32 v117, 0xffff0000, v147
	v_pk_add_f32 v[110:111], v[96:97], v[114:115]
	v_mul_f32_e32 v96, v101, v101
	v_mul_f32_e32 v97, v103, v103
	v_pk_add_f32 v[108:109], v[98:99], v[116:117]
	v_fmac_f32_e32 v96, v100, v100
	v_fmac_f32_e32 v97, v102, v102
	v_add_f32_e32 v96, v96, v97
	v_mul_f32_e32 v97, v111, v111
	v_mul_f32_e32 v98, v109, v109
	v_fmac_f32_e32 v97, v110, v110
	v_fmac_f32_e32 v98, v108, v108
	v_add_f32_e32 v97, v97, v98
	v_add_f32_e32 v96, v96, v97
	v_add_f32_e32 v99, v113, v96
	v_mov_b32_e32 v113, v99
	s_nop 1
	v_permlane16_swap_b32_e32 v99, v113
	v_lshl_add_u64 v[96:97], s[76:77], 0, v[198:199]
	v_lshl_add_u64 v[114:115], v[182:183], 1, v[96:97]
	global_store_dwordx4 v[114:115], v[104:107], off
	v_cvt_pk_bf16_f32 v98, v100, v101
	s_waitcnt lgkmcnt(0)
	v_add_f32_e32 v96, v99, v113
	v_mov_b32_e32 v97, v96
	s_nop 1
	v_permlane32_swap_b32_e32 v96, v97
	v_cvt_pk_bf16_f32 v99, v102, v103
	v_cvt_pk_bf16_f32 v100, v110, v111
	v_cvt_pk_bf16_f32 v101, v108, v109
	global_store_dwordx4 v[114:115], v[98:101], off offset:256
	s_and_saveexec_b64 s[26:27], s[8:9]
	s_cbranch_execz .LBB0_1237
	v_lshlrev_b64 v[98:99], 6, v[196:197]
	v_lshl_add_u64 v[98:99], s[12:13], 0, v[98:99]
	v_lshl_add_u64 v[98:99], s[24:25], 2, v[98:99]
	s_lshl_b32 s0, s38, 2
	v_lshl_add_u64 v[98:99], v[98:99], 0, s[0:1]
	s_waitcnt lgkmcnt(0)
	v_add_f32_e32 v96, v96, v97
	global_store_dword v[98:99], v96, off
.LBB0_1237:
	s_or_b64 exec, exec, s[26:27]
	v_lshlrev_b32_e32 v96, 16, v140
	s_waitcnt lgkmcnt(0)
	v_and_b32_e32 v97, 0xffff0000, v140
	v_lshlrev_b32_e32 v98, 16, v141
	v_and_b32_e32 v99, 0xffff0000, v141
	v_lshlrev_b32_e32 v100, 16, v142
	v_and_b32_e32 v101, 0xffff0000, v142
	v_pk_add_f32 v[92:93], v[92:93], v[96:97]
	v_pk_add_f32 v[94:95], v[94:95], v[98:99]
	v_pk_add_f32 v[98:99], v[88:89], v[100:101]
	v_cvt_pk_bf16_f32 v88, v92, v93
	v_mul_f32_e32 v93, v93, v93
	v_lshlrev_b32_e32 v102, 16, v143
	v_and_b32_e32 v103, 0xffff0000, v143
	v_fmac_f32_e32 v93, v92, v92
	v_mul_f32_e32 v92, v95, v95
	v_pk_add_f32 v[96:97], v[90:91], v[102:103]
	v_fmac_f32_e32 v92, v94, v94
	v_cvt_pk_bf16_f32 v89, v94, v95
	v_add_f32_e32 v92, v93, v92
	v_mul_f32_e32 v93, v99, v99
	v_mul_f32_e32 v94, v97, v97
	v_fmac_f32_e32 v93, v98, v98
	v_fmac_f32_e32 v94, v96, v96
	v_add_f32_e32 v93, v93, v94
	v_add_f32_e32 v100, v92, v93
	v_lshlrev_b32_e32 v92, 16, v136
	v_and_b32_e32 v93, 0xffff0000, v136
	v_lshlrev_b32_e32 v94, 16, v137
	v_and_b32_e32 v95, 0xffff0000, v137
	v_cvt_pk_bf16_f32 v90, v98, v99
	v_cvt_pk_bf16_f32 v91, v96, v97
	v_lshlrev_b32_e32 v96, 16, v138
	v_and_b32_e32 v97, 0xffff0000, v138
	v_pk_add_f32 v[86:87], v[86:87], v[94:95]
	v_pk_add_f32 v[84:85], v[84:85], v[92:93]
	v_lshlrev_b32_e32 v98, 16, v139
	v_and_b32_e32 v99, 0xffff0000, v139
	v_pk_add_f32 v[94:95], v[80:81], v[96:97]
	v_mul_f32_e32 v80, v85, v85
	v_mul_f32_e32 v81, v87, v87
	v_pk_add_f32 v[92:93], v[82:83], v[98:99]
	v_fmac_f32_e32 v80, v84, v84
	v_fmac_f32_e32 v81, v86, v86
	v_add_f32_e32 v80, v80, v81
	v_mul_f32_e32 v81, v95, v95
	v_mul_f32_e32 v82, v93, v93
	v_fmac_f32_e32 v81, v94, v94
	v_fmac_f32_e32 v82, v92, v92
	v_add_f32_e32 v81, v81, v82
	v_add_f32_e32 v80, v80, v81
	v_add_f32_e32 v83, v100, v80
	v_mov_b32_e32 v98, v83
	s_nop 1
	v_permlane16_swap_b32_e32 v83, v98
	v_lshl_add_u64 v[80:81], s[76:77], 0, v[194:195]
	v_lshl_add_u64 v[96:97], v[182:183], 1, v[80:81]
	global_store_dwordx4 v[96:97], v[88:91], off
	v_cvt_pk_bf16_f32 v82, v84, v85
	s_waitcnt lgkmcnt(0)
	v_add_f32_e32 v80, v83, v98
	v_mov_b32_e32 v81, v80
	s_nop 1
	v_permlane32_swap_b32_e32 v80, v81
	v_cvt_pk_bf16_f32 v83, v86, v87
	v_cvt_pk_bf16_f32 v84, v94, v95
	v_cvt_pk_bf16_f32 v85, v92, v93
	global_store_dwordx4 v[96:97], v[82:85], off offset:256
	s_and_saveexec_b64 s[26:27], s[8:9]
	s_cbranch_execz .LBB0_1239
	v_lshlrev_b64 v[82:83], 6, v[192:193]
	v_lshl_add_u64 v[82:83], s[12:13], 0, v[82:83]
	v_lshl_add_u64 v[82:83], s[24:25], 2, v[82:83]
	s_lshl_b32 s0, s38, 2
	v_lshl_add_u64 v[82:83], v[82:83], 0, s[0:1]
	s_waitcnt lgkmcnt(0)
	v_add_f32_e32 v80, v80, v81
	global_store_dword v[82:83], v80, off
; __device__ __forceinline__ unsigned cvt_pk_bf16(float lo, float hi) { unsigned r; asm volatile("v_cvt_pk_bf16_f32 %0, %1, %2" : "=v"(r) : "v"(lo), "v"(hi)); return r; }
;     __device__ __forceinline__ void operator()(const f32x4 (&acc)[2][2][4][2], const Unit& u, int wr, int wc, int fr, int fq) const {
;     ...
;                     for (int bj = 0; bj < 2; ++bj) xin[0][m][bj] = *(const u32x4*)(xb + (size_t)(row0 + ai * HALF + m * 16) * DM + col0 + bj * HALF);
;         }
; #pragma unroll
;             for (int m = 0; m < 4; ++m) {
;                 const int row = row0 + ai * HALF + m * 16; const size_t off = (size_t)row * DM + col0; float q = 0.f;
; #pragma unroll
;                 for (int bj = 0; bj < 2; ++bj) {
;                     const size_t o2 = off + bj * HALF; f32x4 b0, b1;
;                     if (XI_BF16) bf8_to_f32(xin[0][m][bj], b0, b1); else { b0 = *(const f32x4*)(xi + o2); b1 = *(const f32x4*)(xi + o2 + 4); }
;                     const f32x4 o0 = b0 + acc[ai][bj][m][0] * scale, o1 = b1 + acc[ai][bj][m][1] * scale;
;                     u32x4 w; w.x = cvt_pk_bf16(o0[0], o0[1]); w.y = cvt_pk_bf16(o0[2], o0[3]); w.z = cvt_pk_bf16(o1[0], o1[1]); w.w = cvt_pk_bf16(o1[2], o1[3]);
;                     *(u32x4*)(xb + o2) = w;
;                     q += ((o0[0] * o0[0] + o0[1] * o0[1]) + (o0[2] * o0[2] + o0[3] * o0[3])) + ((o1[0] * o1[0] + o1[1] * o1[1]) + (o1[2] * o1[2] + o1[3] * o1[3]));
;                 }
;                 q += __shfl_xor(q, 16); q += __shfl_xor(q, 32);
;                 if (fq == 0) ssout[(size_t)row * 16 + u.pn * 4 + wc] = q;
.LBB0_1239:
	s_or_b64 exec, exec, s[26:27]
	v_lshlrev_b32_e32 v80, 16, v132
	s_waitcnt lgkmcnt(0)
	v_and_b32_e32 v81, 0xffff0000, v132
	v_lshlrev_b32_e32 v82, 16, v133
	v_and_b32_e32 v83, 0xffff0000, v133
	v_lshlrev_b32_e32 v84, 16, v134
	v_and_b32_e32 v85, 0xffff0000, v134
	v_pk_add_f32 v[76:77], v[76:77], v[80:81]
	v_pk_add_f32 v[78:79], v[78:79], v[82:83]
	v_pk_add_f32 v[82:83], v[72:73], v[84:85]
	v_cvt_pk_bf16_f32 v72, v76, v77
	v_mul_f32_e32 v77, v77, v77
	v_lshlrev_b32_e32 v86, 16, v135
	v_and_b32_e32 v87, 0xffff0000, v135
	v_fmac_f32_e32 v77, v76, v76
	v_mul_f32_e32 v76, v79, v79
	v_pk_add_f32 v[80:81], v[74:75], v[86:87]
	v_fmac_f32_e32 v76, v78, v78
	v_cvt_pk_bf16_f32 v73, v78, v79
	v_add_f32_e32 v76, v77, v76
	v_mul_f32_e32 v77, v83, v83
	v_mul_f32_e32 v78, v81, v81
	v_fmac_f32_e32 v77, v82, v82
	v_fmac_f32_e32 v78, v80, v80
	v_add_f32_e32 v77, v77, v78
	v_add_f32_e32 v84, v76, v77
	v_lshlrev_b32_e32 v76, 16, v128
	v_and_b32_e32 v77, 0xffff0000, v128
	v_lshlrev_b32_e32 v78, 16, v129
	v_and_b32_e32 v79, 0xffff0000, v129
	v_cvt_pk_bf16_f32 v74, v82, v83
	v_cvt_pk_bf16_f32 v75, v80, v81
	v_lshlrev_b32_e32 v80, 16, v130
	v_and_b32_e32 v81, 0xffff0000, v130
	v_pk_add_f32 v[70:71], v[70:71], v[78:79]
	v_pk_add_f32 v[68:69], v[68:69], v[76:77]
	v_lshlrev_b32_e32 v82, 16, v131
	v_and_b32_e32 v83, 0xffff0000, v131
	v_pk_add_f32 v[78:79], v[64:65], v[80:81]
	v_mul_f32_e32 v64, v69, v69
	v_mul_f32_e32 v65, v71, v71
	v_pk_add_f32 v[76:77], v[66:67], v[82:83]
	v_fmac_f32_e32 v64, v68, v68
	v_fmac_f32_e32 v65, v70, v70
	v_add_f32_e32 v64, v64, v65
	v_mul_f32_e32 v65, v79, v79
	v_mul_f32_e32 v66, v77, v77
	v_fmac_f32_e32 v65, v78, v78
	v_fmac_f32_e32 v66, v76, v76
	v_add_f32_e32 v65, v65, v66
	v_add_f32_e32 v64, v64, v65
	v_add_f32_e32 v67, v84, v64
	v_mov_b32_e32 v82, v67
	s_nop 1
	v_permlane16_swap_b32_e32 v67, v82
	v_lshl_add_u64 v[64:65], s[76:77], 0, v[190:191]
	v_lshl_add_u64 v[80:81], v[182:183], 1, v[64:65]
	global_store_dwordx4 v[80:81], v[72:75], off
	v_cvt_pk_bf16_f32 v66, v68, v69
	s_waitcnt lgkmcnt(0)
	v_add_f32_e32 v64, v67, v82
	v_mov_b32_e32 v65, v64
	s_nop 1
	v_permlane32_swap_b32_e32 v64, v65
	v_cvt_pk_bf16_f32 v67, v70, v71
	v_cvt_pk_bf16_f32 v68, v78, v79
	v_cvt_pk_bf16_f32 v69, v76, v77
	global_store_dwordx4 v[80:81], v[66:69], off offset:256
	s_and_saveexec_b64 s[26:27], s[8:9]
	s_cbranch_execz .LBB0_1241
	v_lshlrev_b64 v[66:67], 6, v[188:189]
	v_lshl_add_u64 v[66:67], s[12:13], 0, v[66:67]
	v_lshl_add_u64 v[66:67], s[24:25], 2, v[66:67]
	s_lshl_b32 s0, s38, 2
	v_lshl_add_u64 v[66:67], v[66:67], 0, s[0:1]
	s_waitcnt lgkmcnt(0)
	v_add_f32_e32 v64, v64, v65
	global_store_dword v[66:67], v64, off
.LBB0_1241:
	s_or_b64 exec, exec, s[26:27]
	v_add_u32_e32 v100, 0x80, v186
	v_ashrrev_i32_e32 v101, 31, v100
	v_lshlrev_b64 v[110:111], 11, v[100:101]
	s_waitcnt lgkmcnt(0)
	v_lshl_add_u64 v[64:65], v[184:185], 0, v[110:111]
	global_load_dwordx4 v[102:105], v[64:65], off
	global_load_dwordx4 v[106:109], v[64:65], off offset:256
	v_add_u32_e32 v96, 0x90, v186
	v_add_u32_e32 v92, 0xa0, v186
	v_add_u32_e32 v88, 0xb0, v186
	v_ashrrev_i32_e32 v97, 31, v96
	v_ashrrev_i32_e32 v93, 31, v92
	v_ashrrev_i32_e32 v89, 31, v88
	v_lshlrev_b64 v[98:99], 11, v[96:97]
	v_lshlrev_b64 v[94:95], 11, v[92:93]
	v_lshlrev_b64 v[90:91], 11, v[88:89]
	v_lshl_add_u64 v[64:65], v[184:185], 0, v[98:99]
	v_lshl_add_u64 v[66:67], v[184:185], 0, v[94:95]
	v_lshl_add_u64 v[114:115], v[184:185], 0, v[90:91]
	global_load_dwordx4 v[84:87], v[64:65], off
	global_load_dwordx4 v[80:83], v[64:65], off offset:256
	global_load_dwordx4 v[76:79], v[66:67], off
	global_load_dwordx4 v[72:75], v[66:67], off offset:256
	global_load_dwordx4 v[68:71], v[114:115], off
	s_nop 0
	global_load_dwordx4 v[64:67], v[114:115], off offset:256
	s_waitcnt vmcnt(7)
	v_lshlrev_b32_e32 v114, 16, v102
	v_and_b32_e32 v115, 0xffff0000, v102
	v_lshlrev_b32_e32 v102, 16, v103
	v_and_b32_e32 v103, 0xffff0000, v103
	v_lshlrev_b32_e32 v116, 16, v104
	v_and_b32_e32 v117, 0xffff0000, v104
	v_lshlrev_b32_e32 v104, 16, v105
	v_and_b32_e32 v105, 0xffff0000, v105
	s_waitcnt vmcnt(6)
	v_lshlrev_b32_e32 v118, 16, v106
	v_and_b32_e32 v119, 0xffff0000, v106
	v_lshlrev_b32_e32 v106, 16, v107
	v_and_b32_e32 v107, 0xffff0000, v107
	v_lshlrev_b32_e32 v120, 16, v108
	v_and_b32_e32 v121, 0xffff0000, v108
	v_lshlrev_b32_e32 v108, 16, v109
	v_and_b32_e32 v109, 0xffff0000, v109
	v_pk_add_f32 v[62:63], v[62:63], v[102:103]
	v_pk_add_f32 v[60:61], v[60:61], v[114:115]
	v_pk_add_f32 v[58:59], v[58:59], v[104:105]
	v_pk_add_f32 v[56:57], v[56:57], v[116:117]
	v_pk_add_f32 v[54:55], v[54:55], v[106:107]
	v_pk_add_f32 v[52:53], v[52:53], v[118:119]
	v_pk_add_f32 v[102:103], v[50:51], v[108:109]
	v_pk_add_f32 v[104:105], v[48:49], v[120:121]
	v_cvt_pk_bf16_f32 v48, v60, v61
	v_cvt_pk_bf16_f32 v49, v62, v63
	v_cvt_pk_bf16_f32 v50, v56, v57
	v_cvt_pk_bf16_f32 v51, v58, v59
	v_mul_f32_e32 v61, v61, v61
	v_mul_f32_e32 v63, v63, v63
	v_mul_f32_e32 v57, v57, v57
	v_mul_f32_e32 v59, v59, v59
	v_mul_f32_e32 v106, v53, v53
	v_mul_f32_e32 v107, v55, v55
	v_mul_f32_e32 v108, v105, v105
	v_mul_f32_e32 v109, v103, v103
	v_fmac_f32_e32 v61, v60, v60
	v_fmac_f32_e32 v63, v62, v62
	v_fmac_f32_e32 v57, v56, v56
	v_fmac_f32_e32 v59, v58, v58
	v_fmac_f32_e32 v106, v52, v52
	v_fmac_f32_e32 v107, v54, v54
	v_fmac_f32_e32 v108, v104, v104
	v_fmac_f32_e32 v109, v102, v102
	v_add_f32_e32 v56, v61, v63
	v_add_f32_e32 v57, v57, v59
	v_add_f32_e32 v58, v106, v107
	v_add_f32_e32 v59, v108, v109
	v_add_f32_e32 v56, v56, v57
	v_add_f32_e32 v57, v58, v59
	v_add_f32_e32 v58, v56, v57
	v_mov_b32_e32 v59, v58
	s_nop 1
	v_permlane16_swap_b32_e32 v58, v59
	v_lshl_add_u64 v[56:57], s[76:77], 0, v[110:111]
	v_lshl_add_u64 v[56:57], v[182:183], 1, v[56:57]
	global_store_dwordx4 v[56:57], v[48:51], off
	s_waitcnt lgkmcnt(0)
	s_nop 0
	v_add_f32_e32 v48, v58, v59
	v_mov_b32_e32 v49, v48
	s_nop 1
	v_permlane32_swap_b32_e32 v48, v49
	v_cvt_pk_bf16_f32 v50, v52, v53
	v_cvt_pk_bf16_f32 v51, v54, v55
	v_cvt_pk_bf16_f32 v52, v104, v105
	v_cvt_pk_bf16_f32 v53, v102, v103
	global_store_dwordx4 v[56:57], v[50:53], off offset:256
	s_and_saveexec_b64 s[26:27], s[8:9]
	s_cbranch_execz .LBB0_1243
	v_lshlrev_b64 v[50:51], 6, v[100:101]
	v_lshl_add_u64 v[50:51], s[12:13], 0, v[50:51]
	v_lshl_add_u64 v[50:51], s[24:25], 2, v[50:51]
	s_lshl_b32 s0, s38, 2
	v_lshl_add_u64 v[50:51], v[50:51], 0, s[0:1]
	s_waitcnt lgkmcnt(0)
	v_add_f32_e32 v48, v48, v49
	global_store_dword v[50:51], v48, off
; __device__ __forceinline__ unsigned cvt_pk_bf16(float lo, float hi) { unsigned r; asm volatile("v_cvt_pk_bf16_f32 %0, %1, %2" : "=v"(r) : "v"(lo), "v"(hi)); return r; }
;     __device__ __forceinline__ void operator()(const f32x4 (&acc)[2][2][4][2], const Unit& u, int wr, int wc, int fr, int fq) const {
;     ...
; #pragma unroll
;             for (int m = 0; m < 4; ++m) {
;                 const int row = row0 + ai * HALF + m * 16; const size_t off = (size_t)row * DM + col0; float q = 0.f;
; #pragma unroll
;                 for (int bj = 0; bj < 2; ++bj) {
;                     const size_t o2 = off + bj * HALF; f32x4 b0, b1;
;                     if (XI_BF16) bf8_to_f32(xin[0][m][bj], b0, b1); else { b0 = *(const f32x4*)(xi + o2); b1 = *(const f32x4*)(xi + o2 + 4); }
;                     const f32x4 o0 = b0 + acc[ai][bj][m][0] * scale, o1 = b1 + acc[ai][bj][m][1] * scale;
;                     u32x4 w; w.x = cvt_pk_bf16(o0[0], o0[1]); w.y = cvt_pk_bf16(o0[2], o0[3]); w.z = cvt_pk_bf16(o1[0], o1[1]); w.w = cvt_pk_bf16(o1[2], o1[3]);
;                     *(u32x4*)(xb + o2) = w;
;                     q += ((o0[0] * o0[0] + o0[1] * o0[1]) + (o0[2] * o0[2] + o0[3] * o0[3])) + ((o1[0] * o1[0] + o1[1] * o1[1]) + (o1[2] * o1[2] + o1[3] * o1[3]));
;                 }
;                 q += __shfl_xor(q, 16); q += __shfl_xor(q, 32);
;                 if (fq == 0) ssout[(size_t)row * 16 + u.pn * 4 + wc] = q;
.LBB0_1243:
	s_or_b64 exec, exec, s[26:27]
	s_waitcnt vmcnt(7)
	v_lshlrev_b32_e32 v48, 16, v84
	s_waitcnt lgkmcnt(0)
	v_and_b32_e32 v49, 0xffff0000, v84
	v_lshlrev_b32_e32 v50, 16, v85
	v_and_b32_e32 v51, 0xffff0000, v85
	v_lshlrev_b32_e32 v52, 16, v86
	v_and_b32_e32 v53, 0xffff0000, v86
	v_pk_add_f32 v[44:45], v[44:45], v[48:49]
	v_pk_add_f32 v[46:47], v[46:47], v[50:51]
	v_pk_add_f32 v[50:51], v[40:41], v[52:53]
	v_cvt_pk_bf16_f32 v40, v44, v45
	v_mul_f32_e32 v45, v45, v45
	v_lshlrev_b32_e32 v54, 16, v87
	v_and_b32_e32 v55, 0xffff0000, v87
	v_fmac_f32_e32 v45, v44, v44
	v_mul_f32_e32 v44, v47, v47
	v_pk_add_f32 v[48:49], v[42:43], v[54:55]
	v_fmac_f32_e32 v44, v46, v46
	v_cvt_pk_bf16_f32 v41, v46, v47
	v_add_f32_e32 v44, v45, v44
	v_mul_f32_e32 v45, v51, v51
	v_mul_f32_e32 v46, v49, v49
	v_fmac_f32_e32 v45, v50, v50
	v_fmac_f32_e32 v46, v48, v48
	v_add_f32_e32 v45, v45, v46
	v_add_f32_e32 v52, v44, v45
	s_waitcnt vmcnt(6)
	v_lshlrev_b32_e32 v44, 16, v80
	v_and_b32_e32 v45, 0xffff0000, v80
	v_lshlrev_b32_e32 v46, 16, v81
	v_and_b32_e32 v47, 0xffff0000, v81
	v_cvt_pk_bf16_f32 v42, v50, v51
	v_cvt_pk_bf16_f32 v43, v48, v49
	v_lshlrev_b32_e32 v48, 16, v82
	v_and_b32_e32 v49, 0xffff0000, v82
	v_pk_add_f32 v[38:39], v[38:39], v[46:47]
	v_pk_add_f32 v[36:37], v[36:37], v[44:45]
	v_lshlrev_b32_e32 v50, 16, v83
	v_and_b32_e32 v51, 0xffff0000, v83
	v_pk_add_f32 v[46:47], v[32:33], v[48:49]
	v_mul_f32_e32 v32, v37, v37
	v_mul_f32_e32 v33, v39, v39
	v_pk_add_f32 v[44:45], v[34:35], v[50:51]
	v_fmac_f32_e32 v32, v36, v36
	v_fmac_f32_e32 v33, v38, v38
	v_add_f32_e32 v32, v32, v33
	v_mul_f32_e32 v33, v47, v47
	v_mul_f32_e32 v34, v45, v45
	v_fmac_f32_e32 v33, v46, v46
	v_fmac_f32_e32 v34, v44, v44
	v_add_f32_e32 v33, v33, v34
	v_add_f32_e32 v32, v32, v33
	v_add_f32_e32 v35, v52, v32
	v_mov_b32_e32 v50, v35
	s_nop 1
	v_permlane16_swap_b32_e32 v35, v50
	v_lshl_add_u64 v[32:33], s[76:77], 0, v[98:99]
	v_lshl_add_u64 v[48:49], v[182:183], 1, v[32:33]
	global_store_dwordx4 v[48:49], v[40:43], off
	v_cvt_pk_bf16_f32 v34, v36, v37
	s_waitcnt lgkmcnt(0)
	v_add_f32_e32 v32, v35, v50
	v_mov_b32_e32 v33, v32
	s_nop 1
	v_permlane32_swap_b32_e32 v32, v33
	v_cvt_pk_bf16_f32 v35, v38, v39
	v_cvt_pk_bf16_f32 v36, v46, v47
	v_cvt_pk_bf16_f32 v37, v44, v45
	global_store_dwordx4 v[48:49], v[34:37], off offset:256
	s_and_saveexec_b64 s[26:27], s[8:9]
	s_cbranch_execz .LBB0_1245
	v_lshlrev_b64 v[34:35], 6, v[96:97]
	v_lshl_add_u64 v[34:35], s[12:13], 0, v[34:35]
	v_lshl_add_u64 v[34:35], s[24:25], 2, v[34:35]
	s_lshl_b32 s0, s38, 2
	v_lshl_add_u64 v[34:35], v[34:35], 0, s[0:1]
	s_waitcnt lgkmcnt(0)
	v_add_f32_e32 v32, v32, v33
	global_store_dword v[34:35], v32, off
; __device__ __forceinline__ unsigned cvt_pk_bf16(float lo, float hi) { unsigned r; asm volatile("v_cvt_pk_bf16_f32 %0, %1, %2" : "=v"(r) : "v"(lo), "v"(hi)); return r; }
;     __device__ __forceinline__ void operator()(const f32x4 (&acc)[2][2][4][2], const Unit& u, int wr, int wc, int fr, int fq) const {
;     ...
; #pragma unroll
;             for (int m = 0; m < 4; ++m) {
;                 const int row = row0 + ai * HALF + m * 16; const size_t off = (size_t)row * DM + col0; float q = 0.f;
; #pragma unroll
;                 for (int bj = 0; bj < 2; ++bj) {
;                     const size_t o2 = off + bj * HALF; f32x4 b0, b1;
;                     if (XI_BF16) bf8_to_f32(xin[0][m][bj], b0, b1); else { b0 = *(const f32x4*)(xi + o2); b1 = *(const f32x4*)(xi + o2 + 4); }
;                     const f32x4 o0 = b0 + acc[ai][bj][m][0] * scale, o1 = b1 + acc[ai][bj][m][1] * scale;
;                     u32x4 w; w.x = cvt_pk_bf16(o0[0], o0[1]); w.y = cvt_pk_bf16(o0[2], o0[3]); w.z = cvt_pk_bf16(o1[0], o1[1]); w.w = cvt_pk_bf16(o1[2], o1[3]);
;                     *(u32x4*)(xb + o2) = w;
;                     q += ((o0[0] * o0[0] + o0[1] * o0[1]) + (o0[2] * o0[2] + o0[3] * o0[3])) + ((o1[0] * o1[0] + o1[1] * o1[1]) + (o1[2] * o1[2] + o1[3] * o1[3]));
;                 }
;                 q += __shfl_xor(q, 16); q += __shfl_xor(q, 32);
;                 if (fq == 0) ssout[(size_t)row * 16 + u.pn * 4 + wc] = q;
.LBB0_1245:
	s_or_b64 exec, exec, s[26:27]
	s_waitcnt vmcnt(7)
	v_lshlrev_b32_e32 v32, 16, v76
	s_waitcnt lgkmcnt(0)
	v_and_b32_e32 v33, 0xffff0000, v76
	v_lshlrev_b32_e32 v34, 16, v77
	v_and_b32_e32 v35, 0xffff0000, v77
	v_lshlrev_b32_e32 v36, 16, v78
	v_and_b32_e32 v37, 0xffff0000, v78
	v_pk_add_f32 v[28:29], v[28:29], v[32:33]
	v_pk_add_f32 v[30:31], v[30:31], v[34:35]
	v_pk_add_f32 v[34:35], v[24:25], v[36:37]
	v_cvt_pk_bf16_f32 v24, v28, v29
	v_mul_f32_e32 v29, v29, v29
	v_lshlrev_b32_e32 v38, 16, v79
	v_and_b32_e32 v39, 0xffff0000, v79
	v_fmac_f32_e32 v29, v28, v28
	v_mul_f32_e32 v28, v31, v31
	v_pk_add_f32 v[32:33], v[26:27], v[38:39]
	v_fmac_f32_e32 v28, v30, v30
	v_cvt_pk_bf16_f32 v25, v30, v31
	v_add_f32_e32 v28, v29, v28
	v_mul_f32_e32 v29, v35, v35
	v_mul_f32_e32 v30, v33, v33
	v_fmac_f32_e32 v29, v34, v34
	v_fmac_f32_e32 v30, v32, v32
	v_add_f32_e32 v29, v29, v30
	v_add_f32_e32 v36, v28, v29
	s_waitcnt vmcnt(6)
	v_lshlrev_b32_e32 v28, 16, v72
	v_and_b32_e32 v29, 0xffff0000, v72
	v_lshlrev_b32_e32 v30, 16, v73
	v_and_b32_e32 v31, 0xffff0000, v73
	v_cvt_pk_bf16_f32 v26, v34, v35
	v_cvt_pk_bf16_f32 v27, v32, v33
	v_lshlrev_b32_e32 v32, 16, v74
	v_and_b32_e32 v33, 0xffff0000, v74
	v_pk_add_f32 v[22:23], v[22:23], v[30:31]
	v_pk_add_f32 v[20:21], v[20:21], v[28:29]
	v_lshlrev_b32_e32 v34, 16, v75
	v_and_b32_e32 v35, 0xffff0000, v75
	v_pk_add_f32 v[30:31], v[16:17], v[32:33]
	v_mul_f32_e32 v16, v21, v21
	v_mul_f32_e32 v17, v23, v23
	v_pk_add_f32 v[28:29], v[18:19], v[34:35]
	v_fmac_f32_e32 v16, v20, v20
	v_fmac_f32_e32 v17, v22, v22
	v_add_f32_e32 v16, v16, v17
	v_mul_f32_e32 v17, v31, v31
	v_mul_f32_e32 v18, v29, v29
	v_fmac_f32_e32 v17, v30, v30
	v_fmac_f32_e32 v18, v28, v28
	v_add_f32_e32 v17, v17, v18
	v_add_f32_e32 v16, v16, v17
	v_add_f32_e32 v19, v36, v16
	v_mov_b32_e32 v34, v19
	s_nop 1
	v_permlane16_swap_b32_e32 v19, v34
	v_lshl_add_u64 v[16:17], s[76:77], 0, v[94:95]
	v_lshl_add_u64 v[32:33], v[182:183], 1, v[16:17]
	global_store_dwordx4 v[32:33], v[24:27], off
	v_cvt_pk_bf16_f32 v18, v20, v21
	s_waitcnt lgkmcnt(0)
	v_add_f32_e32 v16, v19, v34
	v_mov_b32_e32 v17, v16
	s_nop 1
	v_permlane32_swap_b32_e32 v16, v17
	v_cvt_pk_bf16_f32 v19, v22, v23
	v_cvt_pk_bf16_f32 v20, v30, v31
	v_cvt_pk_bf16_f32 v21, v28, v29
	global_store_dwordx4 v[32:33], v[18:21], off offset:256
	s_and_saveexec_b64 s[26:27], s[8:9]
	s_cbranch_execz .LBB0_1247
	v_lshlrev_b64 v[18:19], 6, v[92:93]
	v_lshl_add_u64 v[18:19], s[12:13], 0, v[18:19]
	v_lshl_add_u64 v[18:19], s[24:25], 2, v[18:19]
	s_lshl_b32 s0, s38, 2
	v_lshl_add_u64 v[18:19], v[18:19], 0, s[0:1]
	s_waitcnt lgkmcnt(0)
	v_add_f32_e32 v16, v16, v17
	global_store_dword v[18:19], v16, off
.LBB0_1247:
	s_or_b64 exec, exec, s[26:27]
	s_waitcnt vmcnt(7)
	v_lshlrev_b32_e32 v16, 16, v68
	s_waitcnt lgkmcnt(0)
	v_and_b32_e32 v17, 0xffff0000, v68
	v_lshlrev_b32_e32 v18, 16, v69
	v_and_b32_e32 v19, 0xffff0000, v69
	v_lshlrev_b32_e32 v20, 16, v70
	v_and_b32_e32 v21, 0xffff0000, v70
	v_pk_add_f32 v[12:13], v[12:13], v[16:17]
	v_pk_add_f32 v[14:15], v[14:15], v[18:19]
	v_pk_add_f32 v[18:19], v[8:9], v[20:21]
	v_cvt_pk_bf16_f32 v8, v12, v13
	v_mul_f32_e32 v13, v13, v13
	v_lshlrev_b32_e32 v22, 16, v71
	v_and_b32_e32 v23, 0xffff0000, v71
	v_fmac_f32_e32 v13, v12, v12
	v_mul_f32_e32 v12, v15, v15
	v_pk_add_f32 v[16:17], v[10:11], v[22:23]
	v_fmac_f32_e32 v12, v14, v14
	v_cvt_pk_bf16_f32 v9, v14, v15
	v_add_f32_e32 v12, v13, v12
	v_mul_f32_e32 v13, v19, v19
	v_mul_f32_e32 v14, v17, v17
	v_fmac_f32_e32 v13, v18, v18
	v_fmac_f32_e32 v14, v16, v16
	v_add_f32_e32 v13, v13, v14
	v_add_f32_e32 v20, v12, v13
	s_waitcnt vmcnt(6)
	v_lshlrev_b32_e32 v12, 16, v64
	v_and_b32_e32 v13, 0xffff0000, v64
	v_lshlrev_b32_e32 v14, 16, v65
	v_and_b32_e32 v15, 0xffff0000, v65
	v_cvt_pk_bf16_f32 v10, v18, v19
	v_cvt_pk_bf16_f32 v11, v16, v17
	v_lshlrev_b32_e32 v16, 16, v66
	v_and_b32_e32 v17, 0xffff0000, v66
	v_pk_add_f32 v[6:7], v[6:7], v[14:15]
	v_pk_add_f32 v[4:5], v[4:5], v[12:13]
	v_lshlrev_b32_e32 v18, 16, v67
	v_and_b32_e32 v19, 0xffff0000, v67
	v_pk_add_f32 v[14:15], v[0:1], v[16:17]
	v_mul_f32_e32 v0, v5, v5
	v_mul_f32_e32 v1, v7, v7
	v_pk_add_f32 v[12:13], v[2:3], v[18:19]
	v_fmac_f32_e32 v0, v4, v4
	v_fmac_f32_e32 v1, v6, v6
	v_add_f32_e32 v0, v0, v1
	v_mul_f32_e32 v1, v15, v15
	v_mul_f32_e32 v2, v13, v13
	v_fmac_f32_e32 v1, v14, v14
	v_fmac_f32_e32 v2, v12, v12
	v_add_f32_e32 v1, v1, v2
	v_add_f32_e32 v0, v0, v1
	v_add_f32_e32 v3, v20, v0
	v_mov_b32_e32 v18, v3
	s_nop 1
	v_permlane16_swap_b32_e32 v3, v18
	v_lshl_add_u64 v[0:1], s[76:77], 0, v[90:91]
	v_lshl_add_u64 v[16:17], v[182:183], 1, v[0:1]
	global_store_dwordx4 v[16:17], v[8:11], off
	v_cvt_pk_bf16_f32 v2, v4, v5
	s_waitcnt lgkmcnt(0)
	v_add_f32_e32 v0, v3, v18
	v_mov_b32_e32 v1, v0
	s_nop 1
	v_permlane32_swap_b32_e32 v0, v1
	v_cvt_pk_bf16_f32 v3, v6, v7
	v_cvt_pk_bf16_f32 v4, v14, v15
	v_cvt_pk_bf16_f32 v5, v12, v13
	global_store_dwordx4 v[16:17], v[2:5], off offset:256
	s_and_saveexec_b64 s[26:27], s[8:9]
	s_cbranch_execz .LBB0_1249
	v_lshlrev_b64 v[2:3], 6, v[88:89]
	v_lshl_add_u64 v[2:3], s[12:13], 0, v[2:3]
	v_lshl_add_u64 v[2:3], s[24:25], 2, v[2:3]
	s_lshl_b32 s0, s38, 2
	v_lshl_add_u64 v[2:3], v[2:3], 0, s[0:1]
	s_waitcnt lgkmcnt(0)
	v_add_f32_e32 v0, v0, v1
	global_store_dword v[2:3], v0, off
